# v070 + mixer latency edits: no full drain before the attention loop, row-scale reads and gMLP fragment reads software-pipelined, norm_store stores de-serialised
# baseline (speedup 1.0000x reference)
.LBB0_520:
	s_or_b64 exec, exec, s[12:13]
	v_and_b32_e32 v14, 31, v84
	s_add_i32 s4, 0, 0x23000
	v_lshl_add_u32 v16, v14, 2, s4
	s_waitcnt lgkmcnt(0)
	s_barrier
	ds_read2st64_b32 v[12:13], v16 offset1:1
	v_lshl_add_u32 v15, v123, 3, s77
	v_lshlrev_b32_e32 v18, 4, v84
	s_waitcnt lgkmcnt(0)
	v_add_f32_e32 v12, 0, v12
	v_add_f32_e32 v17, v12, v13
	ds_read2st64_b32 v[12:13], v16 offset0:2 offset1:3
	s_waitcnt lgkmcnt(0)
	v_add_f32_e32 v12, v17, v12
	v_add_f32_e32 v17, v12, v13
	ds_read2st64_b32 v[12:13], v16 offset0:4 offset1:5
	s_waitcnt lgkmcnt(0)
	v_add_f32_e32 v12, v17, v12
	v_add_f32_e32 v17, v12, v13
	ds_read2st64_b32 v[12:13], v16 offset0:6 offset1:7
	s_waitcnt lgkmcnt(0)
	v_add_f32_e32 v12, v17, v12
	v_add_f32_e32 v12, v12, v13
	v_fmamk_f32 v12, v12, 0x3b000000, v193
	v_rsq_f32_e32 v16, v12
	v_lshl_add_u32 v17, v14, 7, v15
	v_or_b32_e32 v14, 32, v14
	v_mul_f32_e32 v2, v2, v16
	v_mul_f32_e32 v12, v98, v16
	s_waitcnt vmcnt(7)
	v_mul_f32_e32 v2, v64, v2
	v_mul_f32_e32 v12, v65, v12
	v_cvt_pk_bf16_f32 v12, v2, v12
	v_mul_f32_e32 v2, v100, v16
	v_mul_f32_e32 v13, v99, v16
	v_mul_f32_e32 v2, v66, v2
	v_mul_f32_e32 v13, v67, v13
	v_cvt_pk_bf16_f32 v13, v2, v13
	v_and_b32_e32 v2, 0x70, v18
	v_add_u32_e32 v19, v17, v2
	ds_write_b64 v19, v[12:13]
	v_mul_f32_e32 v12, v102, v16
	v_mul_f32_e32 v13, v96, v16
	s_waitcnt vmcnt(6)
	v_mul_f32_e32 v12, v60, v12
	v_mul_f32_e32 v13, v61, v13
	v_cvt_pk_bf16_f32 v12, v12, v13
	v_mul_f32_e32 v13, v115, v16
	v_mul_f32_e32 v19, v116, v16
	v_mul_f32_e32 v13, v62, v13
	v_mul_f32_e32 v19, v63, v19
	v_cvt_pk_bf16_f32 v13, v13, v19
	v_bitop3_b32 v19, v18, 16, v199 bitop3:0x6c
	v_add_u32_e32 v32, v17, v19
	ds_write_b64 v32, v[12:13]
	v_mul_f32_e32 v12, v111, v16
	v_mul_f32_e32 v13, v112, v16
	s_waitcnt vmcnt(5)
	v_mul_f32_e32 v12, v56, v12
	v_mul_f32_e32 v13, v57, v13
	v_cvt_pk_bf16_f32 v12, v12, v13
	v_mul_f32_e32 v13, v113, v16
	v_mul_f32_e32 v32, v114, v16
	v_mul_f32_e32 v13, v58, v13
	v_mul_f32_e32 v32, v59, v32
	v_cvt_pk_bf16_f32 v13, v13, v32
	v_bitop3_b32 v32, v18, 32, v199 bitop3:0x6c
	v_add_u32_e32 v33, v17, v32
	ds_write_b64 v33, v[12:13]
	v_mul_f32_e32 v12, v107, v16
	v_mul_f32_e32 v13, v108, v16
	s_waitcnt vmcnt(4)
	v_mul_f32_e32 v12, v52, v12
	v_mul_f32_e32 v13, v53, v13
	v_cvt_pk_bf16_f32 v12, v12, v13
	v_mul_f32_e32 v13, v109, v16
	v_mul_f32_e32 v33, v110, v16
	v_mul_f32_e32 v13, v54, v13
	v_mul_f32_e32 v33, v55, v33
	v_cvt_pk_bf16_f32 v13, v13, v33
	v_bitop3_b32 v33, v18, 48, v199 bitop3:0x6c
	v_add_u32_e32 v34, v17, v33
	ds_write_b64 v34, v[12:13]
	v_mul_f32_e32 v12, v103, v16
	v_mul_f32_e32 v13, v104, v16
	s_waitcnt vmcnt(3)
	v_mul_f32_e32 v12, v48, v12
	v_mul_f32_e32 v13, v49, v13
	v_cvt_pk_bf16_f32 v12, v12, v13
	v_mul_f32_e32 v13, v105, v16
	v_mul_f32_e32 v34, v106, v16
	v_mul_f32_e32 v13, v50, v13
	v_mul_f32_e32 v34, v51, v34
	v_cvt_pk_bf16_f32 v13, v13, v34
	v_bitop3_b32 v34, v18, 64, v199 bitop3:0x6c
	v_add_u32_e32 v35, v17, v34
	ds_write_b64 v35, v[12:13]
	v_mul_f32_e32 v12, v93, v16
	v_mul_f32_e32 v13, v94, v16
	s_waitcnt vmcnt(2)
	v_mul_f32_e32 v12, v44, v12
	v_mul_f32_e32 v13, v45, v13
	v_cvt_pk_bf16_f32 v12, v12, v13
	v_mul_f32_e32 v13, v95, v16
	v_mul_f32_e32 v35, v97, v16
	v_mul_f32_e32 v13, v46, v13
	v_mul_f32_e32 v35, v47, v35
	v_cvt_pk_bf16_f32 v13, v13, v35
	v_bitop3_b32 v35, v18, s81, v199 bitop3:0x6c
	v_add_u32_e32 v68, v17, v35
	ds_write_b64 v68, v[12:13]
	v_mul_f32_e32 v12, v90, v16
	v_mul_f32_e32 v13, v91, v16
	s_waitcnt vmcnt(1)
	v_mul_f32_e32 v12, v40, v12
	v_mul_f32_e32 v13, v41, v13
	v_cvt_pk_bf16_f32 v12, v12, v13
	v_mul_f32_e32 v13, v92, v16
	v_mul_f32_e32 v68, v89, v16
	v_mul_f32_e32 v13, v42, v13
	v_mul_f32_e32 v68, v43, v68
	v_cvt_pk_bf16_f32 v13, v13, v68
	v_bitop3_b32 v68, v18, s85, v199 bitop3:0x6c
	v_add_u32_e32 v69, v17, v68
	ds_write_b64 v69, v[12:13]
	v_mul_f32_e32 v12, v85, v16
	v_mul_f32_e32 v13, v86, v16
	s_waitcnt vmcnt(0)
	v_mul_f32_e32 v12, v36, v12
	v_mul_f32_e32 v13, v37, v13
	v_cvt_pk_bf16_f32 v12, v12, v13
	v_mul_f32_e32 v13, v88, v16
	v_mul_f32_e32 v16, v87, v16
	v_mul_f32_e32 v13, v38, v13
	v_mul_f32_e32 v16, v39, v16
	v_cvt_pk_bf16_f32 v13, v13, v16
	v_bitop3_b32 v16, v18, s26, v18 bitop3:0xc
	v_add_u32_e32 v17, v17, v16
	ds_write_b64 v17, v[12:13]
	v_lshl_add_u32 v17, v14, 2, s4
	ds_read2st64_b32 v[12:13], v17 offset1:1
	v_lshl_add_u32 v14, v14, 7, v15
	s_waitcnt lgkmcnt(0)
	v_add_f32_e32 v12, 0, v12
	v_add_f32_e32 v18, v12, v13
	ds_read2st64_b32 v[12:13], v17 offset0:2 offset1:3
	s_waitcnt lgkmcnt(0)
	v_add_f32_e32 v12, v18, v12
	v_add_f32_e32 v18, v12, v13
	ds_read2st64_b32 v[12:13], v17 offset0:4 offset1:5
	s_waitcnt lgkmcnt(0)
	v_add_f32_e32 v12, v18, v12
	v_add_f32_e32 v18, v12, v13
	ds_read2st64_b32 v[12:13], v17 offset0:6 offset1:7
	s_waitcnt lgkmcnt(0)
	v_add_f32_e32 v12, v18, v12
	v_add_f32_e32 v12, v12, v13
	v_fmamk_f32 v12, v12, 0x3b000000, v193
	v_rsq_f32_e32 v17, v12
	s_nop 0
	v_mul_f32_e32 v12, v118, v17
	v_mul_f32_e32 v13, v120, v17
	v_mul_f32_e32 v12, v64, v12
	v_mul_f32_e32 v13, v65, v13
	v_cvt_pk_bf16_f32 v12, v12, v13
	v_mul_f32_e32 v13, v121, v17
	v_mul_f32_e32 v15, v122, v17
	v_mul_f32_e32 v13, v66, v13
	v_mul_f32_e32 v15, v67, v15
	v_cvt_pk_bf16_f32 v13, v13, v15
	v_add_u32_e32 v15, v14, v2
	ds_write_b64 v15, v[12:13]
	v_mul_f32_e32 v12, v80, v17
	v_mul_f32_e32 v13, v81, v17
	v_mul_f32_e32 v12, v60, v12
	v_mul_f32_e32 v13, v61, v13
	v_cvt_pk_bf16_f32 v12, v12, v13
	v_mul_f32_e32 v13, v117, v17
	v_mul_f32_e32 v15, v119, v17
	v_mul_f32_e32 v13, v62, v13
	v_mul_f32_e32 v15, v63, v15
	v_cvt_pk_bf16_f32 v13, v13, v15
	v_add_u32_e32 v15, v14, v19
	ds_write_b64 v15, v[12:13]
	v_mul_f32_e32 v12, v78, v17
	v_mul_f32_e32 v13, v76, v17
	v_mul_f32_e32 v12, v56, v12
	v_mul_f32_e32 v13, v57, v13
	v_cvt_pk_bf16_f32 v12, v12, v13
	v_mul_f32_e32 v13, v79, v17
	v_mul_f32_e32 v15, v77, v17
	v_mul_f32_e32 v13, v58, v13
	v_mul_f32_e32 v15, v59, v15
	v_cvt_pk_bf16_f32 v13, v13, v15
	v_add_u32_e32 v15, v14, v32
	ds_write_b64 v15, v[12:13]
	v_mul_f32_e32 v12, v27, v17
	v_mul_f32_e32 v13, v29, v17
	v_mul_f32_e32 v12, v52, v12
	v_mul_f32_e32 v13, v53, v13
	v_cvt_pk_bf16_f32 v12, v12, v13
	v_mul_f32_e32 v13, v30, v17
	v_mul_f32_e32 v15, v31, v17
	v_mul_f32_e32 v13, v54, v13
	v_mul_f32_e32 v15, v55, v15
	v_cvt_pk_bf16_f32 v13, v13, v15
	v_add_u32_e32 v15, v14, v33
	ds_write_b64 v15, v[12:13]
	v_mul_f32_e32 v12, v23, v17
	v_mul_f32_e32 v13, v25, v17
	v_mul_f32_e32 v12, v48, v12
	v_mul_f32_e32 v13, v49, v13
	v_cvt_pk_bf16_f32 v12, v12, v13
	v_mul_f32_e32 v13, v26, v17
	v_mul_f32_e32 v15, v28, v17
	v_mul_f32_e32 v13, v50, v13
	v_mul_f32_e32 v15, v51, v15
	v_cvt_pk_bf16_f32 v13, v13, v15
	v_add_u32_e32 v15, v14, v34
	ds_write_b64 v15, v[12:13]
	v_mul_f32_e32 v12, v20, v17
	v_mul_f32_e32 v13, v21, v17
	v_mul_f32_e32 v12, v44, v12
	v_mul_f32_e32 v13, v45, v13
	v_cvt_pk_bf16_f32 v12, v12, v13
	v_mul_f32_e32 v13, v22, v17
	v_mul_f32_e32 v15, v24, v17
	v_mul_f32_e32 v13, v46, v13
	v_mul_f32_e32 v15, v47, v15
	v_mul_f32_e32 v7, v7, v17
	v_mul_f32_e32 v4, v4, v17
	v_mul_f32_e32 v5, v5, v17
	v_cvt_pk_bf16_f32 v13, v13, v15
	v_add_u32_e32 v15, v14, v35
	v_mul_f32_e32 v7, v40, v7
	v_mul_f32_e32 v9, v9, v17
	v_mul_f32_e32 v4, v36, v4
	v_mul_f32_e32 v5, v37, v5
	ds_write_b64 v15, v[12:13]
	v_mul_f32_e32 v9, v41, v9
	v_cvt_pk_bf16_f32 v12, v7, v9
	v_mul_f32_e32 v7, v10, v17
	v_cvt_pk_bf16_f32 v4, v4, v5
	v_mul_f32_e32 v5, v6, v17
	v_mul_f32_e32 v6, v8, v17
	v_mul_f32_e32 v7, v42, v7
	v_mul_f32_e32 v9, v11, v17
	v_mul_f32_e32 v5, v38, v5
	v_mul_f32_e32 v6, v39, v6
	v_mul_f32_e32 v9, v43, v9
	v_cvt_pk_bf16_f32 v13, v7, v9
	v_add_u32_e32 v7, v14, v68
	v_cvt_pk_bf16_f32 v5, v5, v6
	v_add_u32_e32 v6, v14, v16
	v_ashrrev_i32_e32 v8, 3, v84
	ds_write_b64 v7, v[12:13]
	ds_write_b64 v6, v[4:5]
	v_xor_b32_e32 v4, v8, v84
	v_lshlrev_b32_e32 v4, 4, v4
	v_and_b32_e32 v4, 0x70, v4
	v_add_u32_e32 v14, s77, v4
	v_lshl_add_u64 v[10:11], s[70:71], 0, v[2:3]
	v_lshl_add_u32 v2, v8, 7, v14
	ds_read_b128 v[20:23], v2
	v_ashrrev_i32_e32 v9, 31, v8
	v_lshlrev_b64 v[52:53], 11, v[8:9]
	v_lshl_add_u64 v[52:53], v[10:11], 0, v[52:53]
	v_add_u32_e32 v12, 8, v8
	v_lshl_add_u32 v2, v12, 7, v14
	ds_read_b128 v[24:27], v2
	v_ashrrev_i32_e32 v13, 31, v12
	v_lshlrev_b64 v[54:55], 11, v[12:13]
	v_lshl_add_u64 v[54:55], v[10:11], 0, v[54:55]
	v_add_u32_e32 v12, 16, v8
	v_lshl_add_u32 v2, v12, 7, v14
	ds_read_b128 v[28:31], v2
	v_ashrrev_i32_e32 v13, 31, v12
	v_lshlrev_b64 v[56:57], 11, v[12:13]
	v_lshl_add_u64 v[56:57], v[10:11], 0, v[56:57]
	v_add_u32_e32 v12, 24, v8
	v_lshl_add_u32 v2, v12, 7, v14
	ds_read_b128 v[32:35], v2
	v_ashrrev_i32_e32 v13, 31, v12
	v_lshlrev_b64 v[58:59], 11, v[12:13]
	v_lshl_add_u64 v[58:59], v[10:11], 0, v[58:59]
	v_add_u32_e32 v12, 32, v8
	v_lshl_add_u32 v2, v12, 7, v14
	ds_read_b128 v[36:39], v2
	v_ashrrev_i32_e32 v13, 31, v12
	v_lshlrev_b64 v[60:61], 11, v[12:13]
	v_lshl_add_u64 v[60:61], v[10:11], 0, v[60:61]
	v_add_u32_e32 v12, 40, v8
	v_lshl_add_u32 v2, v12, 7, v14
	ds_read_b128 v[40:43], v2
	v_ashrrev_i32_e32 v13, 31, v12
	v_lshlrev_b64 v[62:63], 11, v[12:13]
	v_lshl_add_u64 v[62:63], v[10:11], 0, v[62:63]
	v_add_u32_e32 v12, 48, v8
	v_lshl_add_u32 v2, v12, 7, v14
	ds_read_b128 v[44:47], v2
	v_ashrrev_i32_e32 v13, 31, v12
	v_lshlrev_b64 v[64:65], 11, v[12:13]
	v_lshl_add_u64 v[64:65], v[10:11], 0, v[64:65]
	v_add_u32_e32 v12, 56, v8
	v_lshl_add_u32 v2, v12, 7, v14
	ds_read_b128 v[48:51], v2
	v_ashrrev_i32_e32 v13, 31, v12
	v_lshlrev_b64 v[66:67], 11, v[12:13]
	v_lshl_add_u64 v[66:67], v[10:11], 0, v[66:67]
	s_waitcnt lgkmcnt(7)
	global_store_dwordx4 v[52:53], v[20:23], off offset:1024
	s_waitcnt lgkmcnt(6)
	global_store_dwordx4 v[54:55], v[24:27], off offset:1024
	s_waitcnt lgkmcnt(5)
	global_store_dwordx4 v[56:57], v[28:31], off offset:1024
	s_waitcnt lgkmcnt(4)
	global_store_dwordx4 v[58:59], v[32:35], off offset:1024
	s_waitcnt lgkmcnt(3)
	global_store_dwordx4 v[60:61], v[36:39], off offset:1024
	s_waitcnt lgkmcnt(2)
	global_store_dwordx4 v[62:63], v[40:43], off offset:1024
	s_waitcnt lgkmcnt(1)
	global_store_dwordx4 v[64:65], v[44:47], off offset:1024
	s_waitcnt lgkmcnt(0)
	global_store_dwordx4 v[66:67], v[48:51], off offset:1024
	s_load_dword s4, s[22:23], 0x0
	s_waitcnt lgkmcnt(0)
	s_add_i32 s76, s4, s76
	s_cmpk_gt_i32 s76, 0xff
	s_cbranch_scc1 .LBB0_568

.LBB0_523:
	s_ashr_i32 s20, s76, 3
	s_lshl_b32 s9, s20, 6
	s_ashr_i32 s6, s9, 31
	s_add_u32 s72, s4, s9
	s_addc_u32 s73, 0, s6
	v_or_b32_e32 v2, s72, v176
	s_max_i32 s6, s20, 8
	v_mad_u64_u32 v[4:5], s[10:11], v2, s90, v[178:179]
	s_add_i32 s33, s6, -8
	s_lshl_b32 s10, s33, 6
	s_add_i32 s10, s10, s4
	s_mul_hi_u32 s11, s10, 0x1400
	s_mulk_i32 s10, 0x1400
	s_add_u32 s10, s60, s10
	s_addc_u32 s11, s61, s11
	v_mad_i32_i24 v5, s73, v198, v5
	s_add_u32 s12, s10, 0x400
	s_addc_u32 s13, s11, 0
	v_lshl_add_u64 v[6:7], s[10:11], 0, v[180:181]
	global_load_dwordx4 v[114:117], v[4:5], off
	global_load_dwordx4 v[118:121], v[4:5], off offset:32
	global_load_dwordx4 v[122:125], v[4:5], off offset:64
	global_load_dwordx4 v[126:129], v[4:5], off offset:96
	v_add_co_u32_e32 v4, vcc, s86, v4
	v_lshl_add_u64 v[6:7], v[6:7], 0, s[38:39]
	v_lshl_add_u64 v[8:9], s[12:13], 0, v[182:183]
	s_add_i32 s21, s77, 0x400
	v_addc_co_u32_e32 v5, vcc, 0, v5, vcc
	s_mov_b32 m0, s77
	v_lshl_add_u64 v[10:11], v[8:9], 0, s[40:41]
	v_lshl_add_u64 v[12:13], s[12:13], 0, v[180:181]
	s_add_i32 s27, s77, 0x800
	global_load_dwordx4 v[130:133], v[4:5], off
	global_load_dwordx4 v[134:137], v[4:5], off offset:32
	global_load_dwordx4 v[138:141], v[4:5], off offset:64
	global_load_dwordx4 v[142:145], v[4:5], off offset:96
	v_lshl_add_u64 v[14:15], v[12:13], 0, s[42:43]
	global_load_lds_dwordx4 v[6:7], off
	s_mov_b32 m0, s21
	s_add_i32 s34, s77, 0xc00
	global_load_lds_dwordx4 v[10:11], off
	s_mov_b32 m0, s27
	v_lshl_add_u64 v[16:17], v[8:9], 0, s[44:45]
	s_add_i32 s35, s77, 0x1000
	global_load_lds_dwordx4 v[14:15], off
	s_mov_b32 m0, s34
	v_lshl_add_u64 v[18:19], v[12:13], 0, s[46:47]
	s_add_i32 s80, s77, 0x1400
	global_load_lds_dwordx4 v[16:17], off
	s_mov_b32 m0, s35
	v_lshl_add_u64 v[20:21], v[8:9], 0, s[48:49]
	s_add_i32 s82, s77, 0x1800
	global_load_lds_dwordx4 v[18:19], off
	s_mov_b32 m0, s80
	v_lshl_add_u64 v[12:13], v[12:13], 0, s[50:51]
	s_add_i32 s84, s77, 0x1c00
	global_load_lds_dwordx4 v[20:21], off
	s_mov_b32 m0, s82
	v_lshl_add_u64 v[8:9], v[8:9], 0, s[52:53]
	global_load_lds_dwordx4 v[12:13], off
	s_mov_b32 m0, s84
	s_cmp_gt_i32 s33, s20
	global_load_lds_dwordx4 v[8:9], off
	s_mov_b64 s[12:13], -1
	s_cbranch_scc1 .LBB0_546
	s_lshl_b32 s10, s20, 8
	s_lshl_b32 s11, s6, 8
	v_mov_b32_e32 v16, v3
	v_mov_b32_e32 v17, v3
	s_sub_i32 s10, s10, s11
	s_add_i32 s33, s6, -9
	s_lshl_b32 s6, s6, 6
	v_mov_b32_e32 v2, v3
	v_mov_b32_e32 v4, v3
	v_mov_b32_e32 v5, v3
	v_mov_b32_e32 v6, v3
	v_mov_b32_e32 v7, v3
	v_mov_b32_e32 v8, v3
	v_mov_b32_e32 v9, v3
	v_mov_b32_e32 v10, v3
	v_mov_b32_e32 v11, v3
	v_mov_b32_e32 v12, v3
	v_mov_b32_e32 v13, v3
	v_mov_b32_e32 v14, v3
	v_mov_b32_e32 v15, v3
	v_mov_b64_e32 v[32:33], v[16:17]
	v_mov_b64_e32 v[48:49], v[16:17]
	v_mov_b64_e32 v[64:65], v[16:17]
	v_mov_b64_e32 v[80:81], v[16:17]
	v_add_u32_e32 v208, s10, v202
	s_add_i32 s89, s6, 0xfffffe00
	s_sub_i32 s10, 0, s20
	v_mov_b32_e32 v187, 0xff800000
	v_mov_b32_e32 v207, 0
	v_mov_b64_e32 v[30:31], v[14:15]
	v_mov_b64_e32 v[28:29], v[12:13]
	v_mov_b64_e32 v[26:27], v[10:11]
	v_mov_b64_e32 v[24:25], v[8:9]
	v_mov_b64_e32 v[22:23], v[6:7]
	v_mov_b64_e32 v[20:21], v[4:5]
	v_mov_b64_e32 v[18:19], v[2:3]
	v_mov_b64_e32 v[46:47], v[14:15]
	v_mov_b64_e32 v[44:45], v[12:13]
	v_mov_b64_e32 v[42:43], v[10:11]
	v_mov_b64_e32 v[40:41], v[8:9]
	v_mov_b64_e32 v[38:39], v[6:7]
	v_mov_b64_e32 v[36:37], v[4:5]
	v_mov_b64_e32 v[34:35], v[2:3]
	v_mov_b64_e32 v[62:63], v[14:15]
	v_mov_b64_e32 v[60:61], v[12:13]
	v_mov_b64_e32 v[58:59], v[10:11]
	v_mov_b64_e32 v[56:57], v[8:9]
	v_mov_b64_e32 v[54:55], v[6:7]
	v_mov_b64_e32 v[52:53], v[4:5]
	v_mov_b64_e32 v[50:51], v[2:3]
	v_mov_b64_e32 v[78:79], v[14:15]
	v_mov_b64_e32 v[76:77], v[12:13]
	v_mov_b64_e32 v[74:75], v[10:11]
	v_mov_b64_e32 v[72:73], v[8:9]
	v_mov_b64_e32 v[70:71], v[6:7]
	v_mov_b64_e32 v[68:69], v[4:5]
	v_mov_b64_e32 v[66:67], v[2:3]
	v_mov_b32_e32 v2, 0
	v_mov_b32_e32 v17, 0xff800000
.LBB0_525:
	s_add_i32 s11, s33, 1
	s_cmp_ge_i32 s11, s20
	s_cselect_b64 s[12:13], -1, 0
	s_ashr_i32 s6, s89, 31
	s_add_u32 s70, s89, s4
	s_addc_u32 s6, s6, 0
	s_mulk_i32 s6, 0x1400
	v_mad_u64_u32 v[4:5], s[70:71], s70, v198, v[184:185]
	v_add_u32_e32 v5, s6, v5
	v_lshl_add_u64 v[6:7], v[4:5], 0, s[36:37]
	s_add_i32 m0, s77, 0x2000
	s_mov_b64 s[70:71], 0xa800
	global_load_lds_dwordx4 v[6:7], off
	v_lshl_add_u64 v[6:7], v[4:5], 0, s[70:71]
	s_mov_b32 m0, s55
	s_mov_b64 s[70:71], 0x14800
	global_load_lds_dwordx4 v[6:7], off
	v_lshl_add_u64 v[6:7], v[4:5], 0, s[70:71]
	s_add_i32 m0, s77, 0x2800
	s_mov_b64 s[70:71], 0x1e800
	global_load_lds_dwordx4 v[6:7], off
	v_lshl_add_u64 v[6:7], v[4:5], 0, s[70:71]
	s_mov_b32 m0, s56
	s_mov_b64 s[70:71], 0x28800
	global_load_lds_dwordx4 v[6:7], off
	v_lshl_add_u64 v[6:7], v[4:5], 0, s[70:71]
	s_mov_b32 m0, s57
	s_mov_b64 s[70:71], 0x32800
	global_load_lds_dwordx4 v[6:7], off
	v_lshl_add_u64 v[6:7], v[4:5], 0, s[70:71]
	s_mov_b32 m0, s97
	s_mov_b64 s[70:71], 0x3c800
	global_load_lds_dwordx4 v[6:7], off
	v_lshl_add_u64 v[6:7], v[4:5], 0, s[70:71]
	s_add_i32 m0, s77, 0x3800
	s_mov_b64 s[70:71], 0x46800
	global_load_lds_dwordx4 v[6:7], off
	v_lshl_add_u64 v[4:5], v[4:5], 0, s[70:71]
	s_mov_b32 m0, s8
	s_and_b64 vcc, exec, s[12:13]
	global_load_lds_dwordx4 v[4:5], off
	s_waitcnt vmcnt(8)
	ds_read_b128 v[150:153], v203
	ds_read_b128 v[4:7], v203 offset:4096
	ds_read_b128 v[154:157], v204
	ds_read_b128 v[8:11], v204 offset:4096
	ds_read_b128 v[158:161], v205
	ds_read_b128 v[12:15], v205 offset:4096
	ds_read_b128 v[162:165], v206
	ds_read_b128 v[146:149], v206 offset:4096
	s_waitcnt lgkmcnt(0)
	s_cbranch_vccnz .LBB0_527
	s_add_i32 s6, s89, 64
	s_ashr_i32 s70, s6, 31
	s_add_u32 s6, s6, s4
	s_addc_u32 s70, s70, 0
	s_mulk_i32 s70, 0x1400
	s_mul_hi_u32 s71, s6, 0x1400
	s_add_i32 s71, s71, s70
	s_mulk_i32 s6, 0x1400
	s_add_u32 s70, s60, s6
	s_addc_u32 s71, s61, s71
	s_add_u32 s74, s70, 0x400
	v_lshl_add_u64 v[82:83], s[70:71], 0, v[180:181]
	s_mov_b32 m0, s77
	s_addc_u32 s75, s71, 0
	v_lshl_add_u64 v[82:83], v[82:83], 0, s[38:39]
	global_load_lds_dwordx4 v[82:83], off
	v_lshl_add_u64 v[82:83], s[74:75], 0, v[182:183]
	v_lshl_add_u64 v[84:85], v[82:83], 0, s[40:41]
	s_mov_b32 m0, s21
	s_nop 0
	global_load_lds_dwordx4 v[84:85], off
	v_lshl_add_u64 v[84:85], s[74:75], 0, v[180:181]
	v_lshl_add_u64 v[86:87], v[84:85], 0, s[42:43]
	s_mov_b32 m0, s27
	s_nop 0
	global_load_lds_dwordx4 v[86:87], off
	v_lshl_add_u64 v[86:87], v[82:83], 0, s[44:45]
	s_mov_b32 m0, s34
	s_nop 0
	global_load_lds_dwordx4 v[86:87], off
	v_lshl_add_u64 v[86:87], v[84:85], 0, s[46:47]
	s_mov_b32 m0, s35
	v_lshl_add_u64 v[84:85], v[84:85], 0, s[50:51]
	global_load_lds_dwordx4 v[86:87], off
	v_lshl_add_u64 v[86:87], v[82:83], 0, s[48:49]
	s_mov_b32 m0, s80
	v_lshl_add_u64 v[82:83], v[82:83], 0, s[52:53]
	global_load_lds_dwordx4 v[86:87], off
	s_mov_b32 m0, s82
	s_nop 0
	global_load_lds_dwordx4 v[84:85], off
	s_mov_b32 m0, s84
	s_nop 0
	global_load_lds_dwordx4 v[82:83], off

.LBB0_552:
	s_or_b64 exec, exec, s[70:71]
	s_lshl_b64 s[10:11], s[72:73], 11
	s_add_u32 s70, s83, s10
	s_addc_u32 s71, s54, s11
	v_and_b32_e32 v32, 31, v16
	s_add_i32 s6, 0, 0x22800
	v_lshl_add_u32 v2, v32, 2, s6
	s_waitcnt lgkmcnt(0)
	s_barrier
	ds_read2st64_b32 v[30:31], v2 offset1:1
	v_lshl_add_u32 v33, v113, 3, s77
	v_lshlrev_b32_e32 v44, 4, v16
	v_lshl_add_u32 v43, v32, 7, v33
	v_or_b32_e32 v32, 32, v32
	s_waitcnt lgkmcnt(0)
	v_add_f32_e32 v30, 0, v30
	v_add_f32_e32 v42, v30, v31
	ds_read2st64_b32 v[30:31], v2 offset0:2 offset1:3
	v_mov_b32_e32 v157, v177
	s_bitcmp1_b32 s76, 3
	s_cselect_b64 s[74:75], -1, 0
	s_waitcnt lgkmcnt(0)
	v_add_f32_e32 v30, v42, v30
	v_add_f32_e32 v42, v30, v31
	ds_read2st64_b32 v[30:31], v2 offset0:4 offset1:5
	s_waitcnt lgkmcnt(0)
	v_add_f32_e32 v30, v42, v30
	v_add_f32_e32 v42, v30, v31
	ds_read2st64_b32 v[30:31], v2 offset0:6 offset1:7
	s_waitcnt lgkmcnt(0)
	v_add_f32_e32 v2, v42, v30
	v_add_f32_e32 v2, v2, v31
	v_fmamk_f32 v2, v2, 0x3b000000, v193
	v_rsq_f32_e32 v42, v2
	s_nop 0
	v_mul_f32_e32 v2, v101, v42
	v_mul_f32_e32 v30, v102, v42
	s_waitcnt vmcnt(7)
	v_mul_f32_e32 v2, v66, v2
	v_mul_f32_e32 v30, v67, v30
	v_cvt_pk_bf16_f32 v30, v2, v30
	v_mul_f32_e32 v2, v99, v42
	v_mul_f32_e32 v31, v100, v42
	v_mul_f32_e32 v2, v68, v2
	v_mul_f32_e32 v31, v69, v31
	v_cvt_pk_bf16_f32 v31, v2, v31
	v_and_b32_e32 v2, 0x70, v44
	v_add_u32_e32 v45, v43, v2
	ds_write_b64 v45, v[30:31]
	v_mul_f32_e32 v30, v97, v42
	v_mul_f32_e32 v31, v98, v42
	s_waitcnt vmcnt(6)
	v_mul_f32_e32 v30, v62, v30
	v_mul_f32_e32 v31, v63, v31
	v_cvt_pk_bf16_f32 v30, v30, v31
	v_mul_f32_e32 v31, v95, v42
	v_mul_f32_e32 v45, v96, v42
	v_mul_f32_e32 v31, v64, v31
	v_mul_f32_e32 v45, v65, v45
	v_cvt_pk_bf16_f32 v31, v31, v45
	v_bitop3_b32 v45, v44, 16, v199 bitop3:0x6c
	v_add_u32_e32 v46, v43, v45
	ds_write_b64 v46, v[30:31]
	v_mul_f32_e32 v30, v93, v42
	v_mul_f32_e32 v31, v94, v42
	s_waitcnt vmcnt(5)
	v_mul_f32_e32 v30, v58, v30
	v_mul_f32_e32 v31, v59, v31
	v_cvt_pk_bf16_f32 v30, v30, v31
	v_mul_f32_e32 v31, v91, v42
	v_mul_f32_e32 v46, v92, v42
	v_mul_f32_e32 v31, v60, v31
	v_mul_f32_e32 v46, v61, v46
	v_cvt_pk_bf16_f32 v31, v31, v46
	v_bitop3_b32 v46, v44, 32, v199 bitop3:0x6c
	v_add_u32_e32 v47, v43, v46
	ds_write_b64 v47, v[30:31]
	v_mul_f32_e32 v30, v78, v42
	v_mul_f32_e32 v31, v79, v42
	s_waitcnt vmcnt(4)
	v_mul_f32_e32 v30, v54, v30
	v_mul_f32_e32 v31, v55, v31
	v_cvt_pk_bf16_f32 v30, v30, v31
	v_mul_f32_e32 v31, v76, v42
	v_mul_f32_e32 v47, v77, v42
	v_mul_f32_e32 v31, v56, v31
	v_mul_f32_e32 v47, v57, v47
	v_cvt_pk_bf16_f32 v31, v31, v47
	v_bitop3_b32 v47, v44, 48, v199 bitop3:0x6c
	v_add_u32_e32 v48, v43, v47
	ds_write_b64 v48, v[30:31]
	v_mul_f32_e32 v30, v89, v42
	v_mul_f32_e32 v31, v90, v42
	s_waitcnt vmcnt(3)
	v_mul_f32_e32 v30, v50, v30
	v_mul_f32_e32 v31, v51, v31
	v_cvt_pk_bf16_f32 v30, v30, v31
	v_mul_f32_e32 v31, v87, v42
	v_mul_f32_e32 v48, v88, v42
	v_mul_f32_e32 v31, v52, v31
	v_mul_f32_e32 v48, v53, v48
	v_cvt_pk_bf16_f32 v31, v31, v48
	v_bitop3_b32 v48, v44, 64, v199 bitop3:0x6c
	v_add_u32_e32 v49, v43, v48
	ds_write_b64 v49, v[30:31]
	v_mul_f32_e32 v30, v85, v42
	v_mul_f32_e32 v31, v86, v42
	s_waitcnt vmcnt(2)
	v_mul_f32_e32 v30, v12, v30
	v_mul_f32_e32 v31, v13, v31
	v_cvt_pk_bf16_f32 v30, v30, v31
	v_mul_f32_e32 v31, v83, v42
	v_mul_f32_e32 v49, v84, v42
	v_mul_f32_e32 v31, v14, v31
	v_mul_f32_e32 v49, v15, v49
	v_cvt_pk_bf16_f32 v31, v31, v49
	v_bitop3_b32 v49, v44, s81, v199 bitop3:0x6c
	v_add_u32_e32 v76, v43, v49
	ds_write_b64 v76, v[30:31]
	v_mul_f32_e32 v30, v82, v42
	v_mul_f32_e32 v31, v75, v42
	s_waitcnt vmcnt(1)
	v_mul_f32_e32 v30, v8, v30
	v_mul_f32_e32 v31, v9, v31
	v_cvt_pk_bf16_f32 v30, v30, v31
	v_mul_f32_e32 v31, v73, v42
	v_mul_f32_e32 v73, v74, v42
	v_mul_f32_e32 v31, v10, v31
	v_mul_f32_e32 v73, v11, v73
	v_cvt_pk_bf16_f32 v31, v31, v73
	v_bitop3_b32 v73, v44, s85, v199 bitop3:0x6c
	v_add_u32_e32 v74, v43, v73
	ds_write_b64 v74, v[30:31]
	v_mul_f32_e32 v30, v71, v42
	v_mul_f32_e32 v31, v72, v42
	s_waitcnt vmcnt(0)
	v_mul_f32_e32 v30, v4, v30
	v_mul_f32_e32 v31, v5, v31
	v_cvt_pk_bf16_f32 v30, v30, v31
	v_mul_f32_e32 v17, v17, v42
	v_mul_f32_e32 v31, v70, v42
	v_mul_f32_e32 v17, v6, v17
	v_mul_f32_e32 v31, v7, v31
	v_cvt_pk_bf16_f32 v31, v17, v31
	v_bitop3_b32 v17, v44, s26, v44 bitop3:0xc
	v_add_u32_e32 v42, v43, v17
	ds_write_b64 v42, v[30:31]
	v_lshl_add_u32 v42, v32, 2, s6
	ds_read2st64_b32 v[30:31], v42 offset1:1
	v_lshl_add_u32 v32, v32, 7, v33
	s_lshl_b32 s6, s76, 3
	s_and_b32 s20, s6, 64
	s_or_b32 s6, s66, s20
	s_waitcnt lgkmcnt(0)
	v_add_f32_e32 v30, 0, v30
	v_add_f32_e32 v43, v30, v31
	ds_read2st64_b32 v[30:31], v42 offset0:2 offset1:3
	s_waitcnt lgkmcnt(0)
	v_add_f32_e32 v30, v43, v30
	v_add_f32_e32 v43, v30, v31
	ds_read2st64_b32 v[30:31], v42 offset0:4 offset1:5
	s_waitcnt lgkmcnt(0)
	v_add_f32_e32 v30, v43, v30
	v_add_f32_e32 v43, v30, v31
	ds_read2st64_b32 v[30:31], v42 offset0:6 offset1:7
	s_waitcnt lgkmcnt(0)
	v_add_f32_e32 v30, v43, v30
	v_add_f32_e32 v30, v30, v31
	v_fmamk_f32 v30, v30, 0x3b000000, v193
	v_rsq_f32_e32 v42, v30
	s_nop 0
	v_mul_f32_e32 v30, v111, v42
	v_mul_f32_e32 v31, v112, v42
	v_mul_f32_e32 v30, v66, v30
	v_mul_f32_e32 v31, v67, v31
	v_cvt_pk_bf16_f32 v30, v30, v31
	v_mul_f32_e32 v31, v109, v42
	v_mul_f32_e32 v33, v110, v42
	v_mul_f32_e32 v31, v68, v31
	v_mul_f32_e32 v33, v69, v33
	v_cvt_pk_bf16_f32 v31, v31, v33
	v_add_u32_e32 v33, v32, v2
	ds_write_b64 v33, v[30:31]
	v_mul_f32_e32 v30, v107, v42
	v_mul_f32_e32 v31, v108, v42
	v_mul_f32_e32 v30, v62, v30
	v_mul_f32_e32 v31, v63, v31
	v_cvt_pk_bf16_f32 v30, v30, v31
	v_mul_f32_e32 v31, v105, v42
	v_mul_f32_e32 v33, v106, v42
	v_mul_f32_e32 v31, v64, v31
	v_mul_f32_e32 v33, v65, v33
	v_cvt_pk_bf16_f32 v31, v31, v33
	v_add_u32_e32 v33, v32, v45
	ds_write_b64 v33, v[30:31]
	v_mul_f32_e32 v30, v40, v42
	v_mul_f32_e32 v31, v41, v42
	v_mul_f32_e32 v30, v58, v30
	v_mul_f32_e32 v31, v59, v31
	v_cvt_pk_bf16_f32 v30, v30, v31
	v_mul_f32_e32 v31, v38, v42
	v_mul_f32_e32 v33, v39, v42
	v_mul_f32_e32 v28, v28, v42
	v_mul_f32_e32 v29, v29, v42
	v_mul_f32_e32 v26, v26, v42
	v_mul_f32_e32 v31, v60, v31
	v_mul_f32_e32 v33, v61, v33
	v_mul_f32_e32 v28, v54, v28
	v_mul_f32_e32 v29, v55, v29
	v_mul_f32_e32 v26, v56, v26
	v_mul_f32_e32 v27, v27, v42
	v_cvt_pk_bf16_f32 v31, v31, v33
	v_add_u32_e32 v33, v32, v46
	v_cvt_pk_bf16_f32 v28, v28, v29
	v_mul_f32_e32 v27, v57, v27
	v_cvt_pk_bf16_f32 v29, v26, v27
	v_add_u32_e32 v26, v32, v47
	ds_write_b64 v33, v[30:31]
	ds_write_b64 v26, v[28:29]
	v_mul_f32_e32 v26, v103, v42
	v_mul_f32_e32 v27, v104, v42
	v_mul_f32_e32 v26, v50, v26
	v_mul_f32_e32 v27, v51, v27
	v_cvt_pk_bf16_f32 v26, v26, v27
	v_mul_f32_e32 v27, v80, v42
	v_mul_f32_e32 v28, v81, v42
	v_mul_f32_e32 v27, v52, v27
	v_mul_f32_e32 v28, v53, v28
	v_cvt_pk_bf16_f32 v27, v27, v28
	v_add_u32_e32 v28, v32, v48
	ds_write_b64 v28, v[26:27]
	v_mul_f32_e32 v26, v36, v42
	v_mul_f32_e32 v12, v12, v26
	v_mul_f32_e32 v26, v37, v42
	v_mul_f32_e32 v13, v13, v26
	v_cvt_pk_bf16_f32 v12, v12, v13
	v_mul_f32_e32 v13, v34, v42
	v_mul_f32_e32 v13, v14, v13
	v_mul_f32_e32 v14, v35, v42
	v_mul_f32_e32 v14, v15, v14
	v_cvt_pk_bf16_f32 v13, v13, v14
	v_add_u32_e32 v14, v32, v49
	ds_write_b64 v14, v[12:13]
	v_mul_f32_e32 v12, v24, v42
	v_mul_f32_e32 v8, v8, v12
	v_mul_f32_e32 v12, v25, v42
	v_mul_f32_e32 v9, v9, v12
	v_cvt_pk_bf16_f32 v8, v8, v9
	v_mul_f32_e32 v9, v22, v42
	v_mul_f32_e32 v9, v10, v9
	v_mul_f32_e32 v10, v23, v42
	v_mul_f32_e32 v10, v11, v10
	v_cvt_pk_bf16_f32 v9, v9, v10
	v_add_u32_e32 v10, v32, v73
	ds_write_b64 v10, v[8:9]
	v_mul_f32_e32 v8, v20, v42
	v_mul_f32_e32 v4, v4, v8
	v_mul_f32_e32 v8, v21, v42
	v_mul_f32_e32 v5, v5, v8
	v_cvt_pk_bf16_f32 v4, v4, v5
	v_mul_f32_e32 v5, v18, v42
	v_mul_f32_e32 v5, v6, v5
	v_mul_f32_e32 v6, v19, v42
	v_mul_f32_e32 v6, v7, v6
	v_cvt_pk_bf16_f32 v5, v5, v6
	v_add_u32_e32 v6, v32, v17
	v_ashrrev_i32_e32 v8, 3, v16
	ds_write_b64 v6, v[4:5]
	v_xor_b32_e32 v4, v8, v16
	v_lshlrev_b32_e32 v4, 4, v4
	v_and_b32_e32 v4, 0x70, v4
	v_add_u32_e32 v14, s77, v4
	v_lshl_add_u64 v[10:11], s[70:71], 0, v[2:3]
	v_lshl_add_u32 v2, v8, 7, v14
	ds_read_b128 v[20:23], v2
	v_ashrrev_i32_e32 v9, 31, v8
	v_lshlrev_b64 v[52:53], 11, v[8:9]
	v_lshl_add_u64 v[52:53], v[10:11], 0, v[52:53]
	v_add_u32_e32 v12, 8, v8
	v_lshl_add_u32 v2, v12, 7, v14
	ds_read_b128 v[24:27], v2
	v_ashrrev_i32_e32 v13, 31, v12
	v_lshlrev_b64 v[54:55], 11, v[12:13]
	v_lshl_add_u64 v[54:55], v[10:11], 0, v[54:55]
	v_add_u32_e32 v12, 16, v8
	v_lshl_add_u32 v2, v12, 7, v14
	ds_read_b128 v[28:31], v2
	v_ashrrev_i32_e32 v13, 31, v12
	v_lshlrev_b64 v[56:57], 11, v[12:13]
	v_lshl_add_u64 v[56:57], v[10:11], 0, v[56:57]
	v_add_u32_e32 v12, 24, v8
	v_lshl_add_u32 v2, v12, 7, v14
	ds_read_b128 v[32:35], v2
	v_ashrrev_i32_e32 v13, 31, v12
	v_lshlrev_b64 v[58:59], 11, v[12:13]
	v_lshl_add_u64 v[58:59], v[10:11], 0, v[58:59]
	v_add_u32_e32 v12, 32, v8
	v_lshl_add_u32 v2, v12, 7, v14
	ds_read_b128 v[36:39], v2
	v_ashrrev_i32_e32 v13, 31, v12
	v_lshlrev_b64 v[60:61], 11, v[12:13]
	v_lshl_add_u64 v[60:61], v[10:11], 0, v[60:61]
	v_add_u32_e32 v12, 40, v8
	v_lshl_add_u32 v2, v12, 7, v14
	ds_read_b128 v[40:43], v2
	v_ashrrev_i32_e32 v13, 31, v12
	v_lshlrev_b64 v[62:63], 11, v[12:13]
	v_lshl_add_u64 v[62:63], v[10:11], 0, v[62:63]
	v_add_u32_e32 v12, 48, v8
	v_lshl_add_u32 v2, v12, 7, v14
	ds_read_b128 v[44:47], v2
	v_ashrrev_i32_e32 v13, 31, v12
	v_lshlrev_b64 v[64:65], 11, v[12:13]
	v_lshl_add_u64 v[64:65], v[10:11], 0, v[64:65]
	v_add_u32_e32 v12, 56, v8
	v_lshl_add_u32 v2, v12, 7, v14
	ds_read_b128 v[48:51], v2
	v_ashrrev_i32_e32 v13, 31, v12
	v_lshlrev_b64 v[66:67], 11, v[12:13]
	v_lshl_add_u64 v[66:67], v[10:11], 0, v[66:67]
	s_waitcnt lgkmcnt(7)
	global_store_dwordx4 v[52:53], v[20:23], off
	s_waitcnt lgkmcnt(6)
	global_store_dwordx4 v[54:55], v[24:27], off
	s_waitcnt lgkmcnt(5)
	global_store_dwordx4 v[56:57], v[28:31], off
	s_waitcnt lgkmcnt(4)
	global_store_dwordx4 v[58:59], v[32:35], off
	s_waitcnt lgkmcnt(3)
	global_store_dwordx4 v[60:61], v[36:39], off
	s_waitcnt lgkmcnt(2)
	global_store_dwordx4 v[62:63], v[40:43], off
	s_waitcnt lgkmcnt(1)
	global_store_dwordx4 v[64:65], v[44:47], off
	s_waitcnt lgkmcnt(0)
	global_store_dwordx4 v[66:67], v[48:51], off
	v_mov_b64_e32 v[14:15], s[2:3]
	s_nop 0
	v_ashrrev_i32_e32 v158, 3, v157
	v_ashrrev_i32_e32 v159, 31, v158
	v_lshl_add_u64 v[12:13], s[72:73], 0, v[158:159]
	v_and_b32_e32 v22, 7, v157
	v_mad_u64_u32 v[14:15], s[10:11], v12, s90, v[14:15]
	v_lshlrev_b32_e32 v2, 5, v22
	v_mad_i32_i24 v15, v13, s90, v15
	global_load_dwordx4 v[4:7], v2, s[64:65] offset:16
	global_load_dwordx4 v[8:11], v2, s[64:65]
	v_lshl_add_u64 v[12:13], s[58:59], 1, v[14:15]
	v_lshlrev_b32_e32 v2, 4, v22
	v_lshl_add_u64 v[12:13], v[12:13], 0, v[2:3]
	v_add_co_u32_e32 v14, vcc, s87, v12
	global_load_dwordx4 v[68:71], v[12:13], off offset:3072
	s_nop 0
	v_addc_co_u32_e32 v15, vcc, 0, v13, vcc
	global_load_dwordx4 v[72:75], v[14:15], off offset:3072
	v_add_co_u32_e32 v14, vcc, s0, v12
	v_and_b32_e32 v156, 31, v157
	s_nop 0
	v_addc_co_u32_e32 v15, vcc, 0, v13, vcc
	global_load_dwordx4 v[76:79], v[14:15], off offset:3072
	v_add_co_u32_e32 v14, vcc, s88, v12
	s_nop 1
	v_addc_co_u32_e32 v15, vcc, 0, v13, vcc
	global_load_dwordx4 v[80:83], v[14:15], off offset:3072
	v_add_co_u32_e32 v14, vcc, s86, v12
	s_nop 1
	v_addc_co_u32_e32 v15, vcc, 0, v13, vcc
	global_load_dwordx4 v[84:87], v[14:15], off offset:3072
	v_add_co_u32_e32 v14, vcc, s91, v12
	s_nop 1
	v_addc_co_u32_e32 v15, vcc, 0, v13, vcc
	global_load_dwordx4 v[88:91], v[14:15], off offset:3072
	v_add_co_u32_e32 v14, vcc, s1, v12
	s_nop 1
	v_addc_co_u32_e32 v15, vcc, 0, v13, vcc
	v_add_co_u32_e32 v12, vcc, s96, v12
	global_load_dwordx4 v[92:95], v[14:15], off offset:3072
	s_nop 0
	v_addc_co_u32_e32 v13, vcc, 0, v13, vcc
	global_load_dwordx4 v[96:99], v[12:13], off offset:3072
	v_or_b32_e32 v12, s6, v156
	v_mov_b32_e32 v13, s67
	v_ashrrev_i32_e32 v14, 2, v157
	v_lshlrev_b64 v[12:13], 8, v[12:13]
	v_and_b32_e32 v160, -8, v14
	v_lshl_add_u64 v[12:13], s[14:15], 0, v[12:13]
	v_ashrrev_i32_e32 v161, 31, v160
	v_lshl_add_u64 v[20:21], v[160:161], 1, v[12:13]
	v_add_co_u32_e32 v24, vcc, 0x2000, v20
	global_load_dwordx4 v[12:15], v[20:21], off
	s_nop 0
	v_addc_co_u32_e32 v25, vcc, 0, v21, vcc
	global_load_dwordx4 v[16:19], v[24:25], off
	global_load_dwordx4 v[148:151], v[20:21], off offset:32
	global_load_dwordx4 v[152:155], v[24:25], off offset:32
	global_load_dwordx4 v[140:143], v[20:21], off offset:64
	global_load_dwordx4 v[144:147], v[24:25], off offset:64
	global_load_dwordx4 v[132:135], v[20:21], off offset:96
	global_load_dwordx4 v[136:139], v[24:25], off offset:96
	s_and_b64 vcc, exec, s[74:75]
	s_cbranch_vccz .LBB0_554
	v_add_co_u32_e32 v24, vcc, 0x2000, v20
	s_nop 1
	v_addc_co_u32_e32 v25, vcc, 0, v21, vcc
	global_load_dwordx4 v[116:119], v[20:21], off offset:128
	global_load_dwordx4 v[120:123], v[24:25], off offset:128

.LBB0_558:
	s_and_b32 s6, s9, 0xffffff80
	s_ashr_i32 s9, s6, 31
	s_add_u32 s10, s6, s4
	s_addc_u32 s11, s9, 0
	v_lshlrev_b32_e32 v24, 3, v22
	v_lshl_add_u64 v[20:21], s[10:11], 0, v[158:159]
	v_mov_b64_e32 v[22:23], s[2:3]
	v_mad_u64_u32 v[22:23], s[10:11], v20, s90, v[22:23]
	v_mad_i32_i24 v23, v21, s90, v23
	v_lshlrev_b32_e32 v20, 1, v24
	v_mov_b32_e32 v21, v3
	v_lshl_add_u64 v[22:23], s[58:59], 1, v[22:23]
	v_lshl_add_u64 v[28:29], v[22:23], 0, v[20:21]
	v_mov_b32_e32 v20, v28
	v_mov_b32_e32 v21, v29
	v_lshlrev_b32_e32 v159, 7, v158
	v_lshlrev_b32_e32 v24, 5, v158
	v_bitop3_b32 v25, v24, v2, 64 bitop3:0x6c
	v_add3_u32 v44, s77, v25, v159
	v_add_u32_e32 v45, s7, v24
	s_and_b64 vcc, exec, s[12:13]
	s_cbranch_vccnz .Lsgu_single
	v_add_co_u32_e32 v252, vcc, 0x1000, v20
	s_nop 1
	v_addc_co_u32_e32 v253, vcc, 0, v21, vcc
	global_load_dwordx4 v[208:211], v[252:253], off
	v_add_co_u32_e32 v252, vcc, 0xb000, v20
	s_nop 1
	v_addc_co_u32_e32 v253, vcc, 0, v21, vcc
	global_load_dwordx4 v[212:215], v[252:253], off
	v_add_co_u32_e32 v252, vcc, 0x15000, v20
	s_nop 1
	v_addc_co_u32_e32 v253, vcc, 0, v21, vcc
	global_load_dwordx4 v[216:219], v[252:253], off
	v_add_co_u32_e32 v252, vcc, 0x1f000, v20
	s_nop 1
	v_addc_co_u32_e32 v253, vcc, 0, v21, vcc
	global_load_dwordx4 v[220:223], v[252:253], off
	v_add_co_u32_e32 v252, vcc, 0x29000, v20
	s_nop 1
	v_addc_co_u32_e32 v253, vcc, 0, v21, vcc
	global_load_dwordx4 v[224:227], v[252:253], off
	v_add_co_u32_e32 v252, vcc, 0x33000, v20
	s_nop 1
	v_addc_co_u32_e32 v253, vcc, 0, v21, vcc
	global_load_dwordx4 v[228:231], v[252:253], off
	v_add_co_u32_e32 v252, vcc, 0x3d000, v20
	s_nop 1
	v_addc_co_u32_e32 v253, vcc, 0, v21, vcc
	global_load_dwordx4 v[232:235], v[252:253], off
	v_add_co_u32_e32 v252, vcc, 0x47000, v20
	s_nop 1
	v_addc_co_u32_e32 v253, vcc, 0, v21, vcc
	global_load_dwordx4 v[236:239], v[252:253], off
	v_add_co_u32_e32 v252, vcc, 0x51000, v20
	s_nop 1
	v_addc_co_u32_e32 v253, vcc, 0, v21, vcc
	global_load_dwordx4 v[240:243], v[252:253], off
	v_add_co_u32_e32 v252, vcc, 0x5b000, v20
	s_nop 1
	v_addc_co_u32_e32 v253, vcc, 0, v21, vcc
	global_load_dwordx4 v[244:247], v[252:253], off
	v_add_co_u32_e32 v252, vcc, 0x65000, v20
	s_nop 1
	v_addc_co_u32_e32 v253, vcc, 0, v21, vcc
	global_load_dwordx4 v[248:251], v[252:253], off
	v_add_co_u32_e32 v252, vcc, 0x6f000, v20
	s_nop 1
	v_addc_co_u32_e32 v253, vcc, 0, v21, vcc
	global_load_dwordx4 v[32:35], v[252:253], off
	v_add_co_u32_e32 v252, vcc, 0x79000, v20
	s_nop 1
	v_addc_co_u32_e32 v253, vcc, 0, v21, vcc
	global_load_dwordx4 v[36:39], v[252:253], off
	v_add_co_u32_e32 v252, vcc, 0x83000, v20
	s_nop 1
	v_addc_co_u32_e32 v253, vcc, 0, v21, vcc
	global_load_dwordx4 v[40:43], v[252:253], off
	v_add_co_u32_e32 v252, vcc, 0x8d000, v20
	s_nop 1
	v_addc_co_u32_e32 v253, vcc, 0, v21, vcc
	global_load_dwordx4 v[24:27], v[252:253], off
	v_add_co_u32_e32 v252, vcc, 0x97000, v20
	s_nop 1
	v_addc_co_u32_e32 v253, vcc, 0, v21, vcc
	global_load_dwordx4 v[186:189], v[252:253], off
	ds_read_b128 v[28:31], v45
	ds_read_b128 v[168:171], v45 offset:16
	ds_read_b128 v[52:55], v45 offset:256
	ds_read_b128 v[56:59], v45 offset:272
	s_waitcnt lgkmcnt(2)
	v_add_f32_e32 v164, v28, v29
	v_add_f32_e32 v165, v168, v169
	v_add_f32_e32 v166, v30, v31
	v_add_f32_e32 v161, v170, v171
	v_add_f32_e32 v164, v164, v166
	v_add_f32_e32 v165, v165, v161
	v_add_f32_e32 v164, v164, v165
	v_fmamk_f32 v164, v164, 0x3b000000, v193
	v_rsq_f32_e32 v164, v164
	s_waitcnt vmcnt(15)
	v_lshlrev_b32_e32 v46, 16, v208
	v_lshlrev_b32_e32 v47, 16, v209
	v_lshlrev_b32_e32 v48, 16, v210
	v_lshlrev_b32_e32 v163, 16, v211
	v_and_b32_e32 v208, 0xffff0000, v208
	v_and_b32_e32 v209, 0xffff0000, v209
	v_and_b32_e32 v210, 0xffff0000, v210
	v_and_b32_e32 v211, 0xffff0000, v211
	v_mul_f32_e32 v208, v164, v208
	v_mul_f32_e32 v209, v164, v209
	v_mul_f32_e32 v210, v164, v210
	v_mul_f32_e32 v211, v164, v211
	v_mul_f32_e32 v46, v164, v46
	v_mul_f32_e32 v47, v164, v47
	v_mul_f32_e32 v48, v164, v48
	v_mul_f32_e32 v163, v164, v163
	v_mul_f32_e32 v208, v9, v208
	v_mul_f32_e32 v209, v11, v209
	v_mul_f32_e32 v210, v5, v210
	v_mul_f32_e32 v211, v7, v211
	v_mul_f32_e32 v46, v8, v46
	v_mul_f32_e32 v47, v10, v47
	v_mul_f32_e32 v48, v4, v48
	v_mul_f32_e32 v163, v6, v163
	v_cvt_pk_bf16_f32 v208, v46, v208
	v_cvt_pk_bf16_f32 v209, v47, v209
	v_cvt_pk_bf16_f32 v210, v48, v210
	v_cvt_pk_bf16_f32 v211, v163, v211
	ds_write_b128 v44, v[208:211]
	ds_read_b128 v[28:31], v45 offset:512
	ds_read_b128 v[168:171], v45 offset:528
	s_waitcnt lgkmcnt(2)
	v_add_f32_e32 v164, v52, v53
	v_add_f32_e32 v165, v56, v57
	v_add_f32_e32 v166, v54, v55
	v_add_f32_e32 v161, v58, v59
	v_add_f32_e32 v164, v164, v166
	v_add_f32_e32 v165, v165, v161
	v_add_f32_e32 v164, v164, v165
	v_fmamk_f32 v164, v164, 0x3b000000, v193
	v_rsq_f32_e32 v164, v164
	s_waitcnt vmcnt(14)
	v_lshlrev_b32_e32 v46, 16, v212
	v_lshlrev_b32_e32 v47, 16, v213
	v_lshlrev_b32_e32 v48, 16, v214
	v_lshlrev_b32_e32 v163, 16, v215
	v_and_b32_e32 v212, 0xffff0000, v212
	v_and_b32_e32 v213, 0xffff0000, v213
	v_and_b32_e32 v214, 0xffff0000, v214
	v_and_b32_e32 v215, 0xffff0000, v215
	v_mul_f32_e32 v212, v164, v212
	v_mul_f32_e32 v213, v164, v213
	v_mul_f32_e32 v214, v164, v214
	v_mul_f32_e32 v215, v164, v215
	v_mul_f32_e32 v46, v164, v46
	v_mul_f32_e32 v47, v164, v47
	v_mul_f32_e32 v48, v164, v48
	v_mul_f32_e32 v163, v164, v163
	v_mul_f32_e32 v212, v9, v212
	v_mul_f32_e32 v213, v11, v213
	v_mul_f32_e32 v214, v5, v214
	v_mul_f32_e32 v215, v7, v215
	v_mul_f32_e32 v46, v8, v46
	v_mul_f32_e32 v47, v10, v47
	v_mul_f32_e32 v48, v4, v48
	v_mul_f32_e32 v163, v6, v163
	v_cvt_pk_bf16_f32 v212, v46, v212
	v_cvt_pk_bf16_f32 v213, v47, v213
	v_cvt_pk_bf16_f32 v214, v48, v214
	v_cvt_pk_bf16_f32 v215, v163, v215
	ds_write_b128 v44, v[212:215] offset:1024
	ds_read_b128 v[52:55], v45 offset:768
	ds_read_b128 v[56:59], v45 offset:784
	s_waitcnt lgkmcnt(2)
	v_add_f32_e32 v164, v28, v29
	v_add_f32_e32 v165, v168, v169
	v_add_f32_e32 v166, v30, v31
	v_add_f32_e32 v161, v170, v171
	v_add_f32_e32 v164, v164, v166
	v_add_f32_e32 v165, v165, v161
	v_add_f32_e32 v164, v164, v165
	v_fmamk_f32 v164, v164, 0x3b000000, v193
	v_rsq_f32_e32 v164, v164
	s_waitcnt vmcnt(13)
	v_lshlrev_b32_e32 v46, 16, v216
	v_lshlrev_b32_e32 v47, 16, v217
	v_lshlrev_b32_e32 v48, 16, v218
	v_lshlrev_b32_e32 v163, 16, v219
	v_and_b32_e32 v216, 0xffff0000, v216
	v_and_b32_e32 v217, 0xffff0000, v217
	v_and_b32_e32 v218, 0xffff0000, v218
	v_and_b32_e32 v219, 0xffff0000, v219
	v_mul_f32_e32 v216, v164, v216
	v_mul_f32_e32 v217, v164, v217
	v_mul_f32_e32 v218, v164, v218
	v_mul_f32_e32 v219, v164, v219
	v_mul_f32_e32 v46, v164, v46
	v_mul_f32_e32 v47, v164, v47
	v_mul_f32_e32 v48, v164, v48
	v_mul_f32_e32 v163, v164, v163
	v_mul_f32_e32 v216, v9, v216
	v_mul_f32_e32 v217, v11, v217
	v_mul_f32_e32 v218, v5, v218
	v_mul_f32_e32 v219, v7, v219
	v_mul_f32_e32 v46, v8, v46
	v_mul_f32_e32 v47, v10, v47
	v_mul_f32_e32 v48, v4, v48
	v_mul_f32_e32 v163, v6, v163
	v_cvt_pk_bf16_f32 v216, v46, v216
	v_cvt_pk_bf16_f32 v217, v47, v217
	v_cvt_pk_bf16_f32 v218, v48, v218
	v_cvt_pk_bf16_f32 v219, v163, v219
	ds_write_b128 v44, v[216:219] offset:2048
	ds_read_b128 v[28:31], v45 offset:1024
	ds_read_b128 v[168:171], v45 offset:1040
	s_waitcnt lgkmcnt(2)
	v_add_f32_e32 v164, v52, v53
	v_add_f32_e32 v165, v56, v57
	v_add_f32_e32 v166, v54, v55
	v_add_f32_e32 v161, v58, v59
	v_add_f32_e32 v164, v164, v166
	v_add_f32_e32 v165, v165, v161
	v_add_f32_e32 v164, v164, v165
	v_fmamk_f32 v164, v164, 0x3b000000, v193
	v_rsq_f32_e32 v164, v164
	s_waitcnt vmcnt(12)
	v_lshlrev_b32_e32 v46, 16, v220
	v_lshlrev_b32_e32 v47, 16, v221
	v_lshlrev_b32_e32 v48, 16, v222
	v_lshlrev_b32_e32 v163, 16, v223
	v_and_b32_e32 v220, 0xffff0000, v220
	v_and_b32_e32 v221, 0xffff0000, v221
	v_and_b32_e32 v222, 0xffff0000, v222
	v_and_b32_e32 v223, 0xffff0000, v223
	v_mul_f32_e32 v220, v164, v220
	v_mul_f32_e32 v221, v164, v221
	v_mul_f32_e32 v222, v164, v222
	v_mul_f32_e32 v223, v164, v223
	v_mul_f32_e32 v46, v164, v46
	v_mul_f32_e32 v47, v164, v47
	v_mul_f32_e32 v48, v164, v48
	v_mul_f32_e32 v163, v164, v163
	v_mul_f32_e32 v220, v9, v220
	v_mul_f32_e32 v221, v11, v221
	v_mul_f32_e32 v222, v5, v222
	v_mul_f32_e32 v223, v7, v223
	v_mul_f32_e32 v46, v8, v46
	v_mul_f32_e32 v47, v10, v47
	v_mul_f32_e32 v48, v4, v48
	v_mul_f32_e32 v163, v6, v163
	v_cvt_pk_bf16_f32 v220, v46, v220
	v_cvt_pk_bf16_f32 v221, v47, v221
	v_cvt_pk_bf16_f32 v222, v48, v222
	v_cvt_pk_bf16_f32 v223, v163, v223
	ds_write_b128 v44, v[220:223] offset:3072
	ds_read_b128 v[52:55], v45 offset:1280
	ds_read_b128 v[56:59], v45 offset:1296
	s_waitcnt lgkmcnt(2)
	v_add_f32_e32 v164, v28, v29
	v_add_f32_e32 v165, v168, v169
	v_add_f32_e32 v166, v30, v31
	v_add_f32_e32 v161, v170, v171
	v_add_f32_e32 v164, v164, v166
	v_add_f32_e32 v165, v165, v161
	v_add_f32_e32 v164, v164, v165
	v_fmamk_f32 v164, v164, 0x3b000000, v193
	v_rsq_f32_e32 v164, v164
	s_waitcnt vmcnt(11)
	v_lshlrev_b32_e32 v46, 16, v224
	v_lshlrev_b32_e32 v47, 16, v225
	v_lshlrev_b32_e32 v48, 16, v226
	v_lshlrev_b32_e32 v163, 16, v227
	v_and_b32_e32 v224, 0xffff0000, v224
	v_and_b32_e32 v225, 0xffff0000, v225
	v_and_b32_e32 v226, 0xffff0000, v226
	v_and_b32_e32 v227, 0xffff0000, v227
	v_mul_f32_e32 v224, v164, v224
	v_mul_f32_e32 v225, v164, v225
	v_mul_f32_e32 v226, v164, v226
	v_mul_f32_e32 v227, v164, v227
	v_mul_f32_e32 v46, v164, v46
	v_mul_f32_e32 v47, v164, v47
	v_mul_f32_e32 v48, v164, v48
	v_mul_f32_e32 v163, v164, v163
	v_mul_f32_e32 v224, v9, v224
	v_mul_f32_e32 v225, v11, v225
	v_mul_f32_e32 v226, v5, v226
	v_mul_f32_e32 v227, v7, v227
	v_mul_f32_e32 v46, v8, v46
	v_mul_f32_e32 v47, v10, v47
	v_mul_f32_e32 v48, v4, v48
	v_mul_f32_e32 v163, v6, v163
	v_cvt_pk_bf16_f32 v224, v46, v224
	v_cvt_pk_bf16_f32 v225, v47, v225
	v_cvt_pk_bf16_f32 v226, v48, v226
	v_cvt_pk_bf16_f32 v227, v163, v227
	ds_write_b128 v44, v[224:227] offset:4096
	ds_read_b128 v[28:31], v45 offset:1536
	ds_read_b128 v[168:171], v45 offset:1552
	s_waitcnt lgkmcnt(2)
	v_add_f32_e32 v164, v52, v53
	v_add_f32_e32 v165, v56, v57
	v_add_f32_e32 v166, v54, v55
	v_add_f32_e32 v161, v58, v59
	v_add_f32_e32 v164, v164, v166
	v_add_f32_e32 v165, v165, v161
	v_add_f32_e32 v164, v164, v165
	v_fmamk_f32 v164, v164, 0x3b000000, v193
	v_rsq_f32_e32 v164, v164
	s_waitcnt vmcnt(10)
	v_lshlrev_b32_e32 v46, 16, v228
	v_lshlrev_b32_e32 v47, 16, v229
	v_lshlrev_b32_e32 v48, 16, v230
	v_lshlrev_b32_e32 v163, 16, v231
	v_and_b32_e32 v228, 0xffff0000, v228
	v_and_b32_e32 v229, 0xffff0000, v229
	v_and_b32_e32 v230, 0xffff0000, v230
	v_and_b32_e32 v231, 0xffff0000, v231
	v_mul_f32_e32 v228, v164, v228
	v_mul_f32_e32 v229, v164, v229
	v_mul_f32_e32 v230, v164, v230
	v_mul_f32_e32 v231, v164, v231
	v_mul_f32_e32 v46, v164, v46
	v_mul_f32_e32 v47, v164, v47
	v_mul_f32_e32 v48, v164, v48
	v_mul_f32_e32 v163, v164, v163
	v_mul_f32_e32 v228, v9, v228
	v_mul_f32_e32 v229, v11, v229
	v_mul_f32_e32 v230, v5, v230
	v_mul_f32_e32 v231, v7, v231
	v_mul_f32_e32 v46, v8, v46
	v_mul_f32_e32 v47, v10, v47
	v_mul_f32_e32 v48, v4, v48
	v_mul_f32_e32 v163, v6, v163
	v_cvt_pk_bf16_f32 v228, v46, v228
	v_cvt_pk_bf16_f32 v229, v47, v229
	v_cvt_pk_bf16_f32 v230, v48, v230
	v_cvt_pk_bf16_f32 v231, v163, v231
	ds_write_b128 v44, v[228:231] offset:5120
	ds_read_b128 v[52:55], v45 offset:1792
	ds_read_b128 v[56:59], v45 offset:1808
	s_waitcnt lgkmcnt(2)
	v_add_f32_e32 v164, v28, v29
	v_add_f32_e32 v165, v168, v169
	v_add_f32_e32 v166, v30, v31
	v_add_f32_e32 v161, v170, v171
	v_add_f32_e32 v164, v164, v166
	v_add_f32_e32 v165, v165, v161
	v_add_f32_e32 v164, v164, v165
	v_fmamk_f32 v164, v164, 0x3b000000, v193
	v_rsq_f32_e32 v164, v164
	s_waitcnt vmcnt(9)
	v_lshlrev_b32_e32 v46, 16, v232
	v_lshlrev_b32_e32 v47, 16, v233
	v_lshlrev_b32_e32 v48, 16, v234
	v_lshlrev_b32_e32 v163, 16, v235
	v_and_b32_e32 v232, 0xffff0000, v232
	v_and_b32_e32 v233, 0xffff0000, v233
	v_and_b32_e32 v234, 0xffff0000, v234
	v_and_b32_e32 v235, 0xffff0000, v235
	v_mul_f32_e32 v232, v164, v232
	v_mul_f32_e32 v233, v164, v233
	v_mul_f32_e32 v234, v164, v234
	v_mul_f32_e32 v235, v164, v235
	v_mul_f32_e32 v46, v164, v46
	v_mul_f32_e32 v47, v164, v47
	v_mul_f32_e32 v48, v164, v48
	v_mul_f32_e32 v163, v164, v163
	v_mul_f32_e32 v232, v9, v232
	v_mul_f32_e32 v233, v11, v233
	v_mul_f32_e32 v234, v5, v234
	v_mul_f32_e32 v235, v7, v235
	v_mul_f32_e32 v46, v8, v46
	v_mul_f32_e32 v47, v10, v47
	v_mul_f32_e32 v48, v4, v48
	v_mul_f32_e32 v163, v6, v163
	v_cvt_pk_bf16_f32 v232, v46, v232
	v_cvt_pk_bf16_f32 v233, v47, v233
	v_cvt_pk_bf16_f32 v234, v48, v234
	v_cvt_pk_bf16_f32 v235, v163, v235
	ds_write_b128 v44, v[232:235] offset:6144
	ds_read_b128 v[28:31], v45 offset:2048
	ds_read_b128 v[168:171], v45 offset:2064
	s_waitcnt lgkmcnt(2)
	v_add_f32_e32 v164, v52, v53
	v_add_f32_e32 v165, v56, v57
	v_add_f32_e32 v166, v54, v55
	v_add_f32_e32 v161, v58, v59
	v_add_f32_e32 v164, v164, v166
	v_add_f32_e32 v165, v165, v161
	v_add_f32_e32 v164, v164, v165
	v_fmamk_f32 v164, v164, 0x3b000000, v193
	v_rsq_f32_e32 v164, v164
	s_waitcnt vmcnt(8)
	v_lshlrev_b32_e32 v46, 16, v236
	v_lshlrev_b32_e32 v47, 16, v237
	v_lshlrev_b32_e32 v48, 16, v238
	v_lshlrev_b32_e32 v163, 16, v239
	v_and_b32_e32 v236, 0xffff0000, v236
	v_and_b32_e32 v237, 0xffff0000, v237
	v_and_b32_e32 v238, 0xffff0000, v238
	v_and_b32_e32 v239, 0xffff0000, v239
	v_mul_f32_e32 v236, v164, v236
	v_mul_f32_e32 v237, v164, v237
	v_mul_f32_e32 v238, v164, v238
	v_mul_f32_e32 v239, v164, v239
	v_mul_f32_e32 v46, v164, v46
	v_mul_f32_e32 v47, v164, v47
	v_mul_f32_e32 v48, v164, v48
	v_mul_f32_e32 v163, v164, v163
	v_mul_f32_e32 v236, v9, v236
	v_mul_f32_e32 v237, v11, v237
	v_mul_f32_e32 v238, v5, v238
	v_mul_f32_e32 v239, v7, v239
	v_mul_f32_e32 v46, v8, v46
	v_mul_f32_e32 v47, v10, v47
	v_mul_f32_e32 v48, v4, v48
	v_mul_f32_e32 v163, v6, v163
	v_cvt_pk_bf16_f32 v236, v46, v236
	v_cvt_pk_bf16_f32 v237, v47, v237
	v_cvt_pk_bf16_f32 v238, v48, v238
	v_cvt_pk_bf16_f32 v239, v163, v239
	ds_write_b128 v44, v[236:239] offset:7168
	ds_read_b128 v[52:55], v45 offset:2304
	ds_read_b128 v[56:59], v45 offset:2320
	s_waitcnt lgkmcnt(2)
	v_add_f32_e32 v164, v28, v29
	v_add_f32_e32 v165, v168, v169
	v_add_f32_e32 v166, v30, v31
	v_add_f32_e32 v161, v170, v171
	v_add_f32_e32 v164, v164, v166
	v_add_f32_e32 v165, v165, v161
	v_add_f32_e32 v164, v164, v165
	v_fmamk_f32 v164, v164, 0x3b000000, v193
	v_rsq_f32_e32 v164, v164
	s_waitcnt vmcnt(7)
	v_lshlrev_b32_e32 v46, 16, v240
	v_lshlrev_b32_e32 v47, 16, v241
	v_lshlrev_b32_e32 v48, 16, v242
	v_lshlrev_b32_e32 v163, 16, v243
	v_and_b32_e32 v240, 0xffff0000, v240
	v_and_b32_e32 v241, 0xffff0000, v241
	v_and_b32_e32 v242, 0xffff0000, v242
	v_and_b32_e32 v243, 0xffff0000, v243
	v_mul_f32_e32 v240, v164, v240
	v_mul_f32_e32 v241, v164, v241
	v_mul_f32_e32 v242, v164, v242
	v_mul_f32_e32 v243, v164, v243
	v_mul_f32_e32 v46, v164, v46
	v_mul_f32_e32 v47, v164, v47
	v_mul_f32_e32 v48, v164, v48
	v_mul_f32_e32 v163, v164, v163
	v_mul_f32_e32 v240, v9, v240
	v_mul_f32_e32 v241, v11, v241
	v_mul_f32_e32 v242, v5, v242
	v_mul_f32_e32 v243, v7, v243
	v_mul_f32_e32 v46, v8, v46
	v_mul_f32_e32 v47, v10, v47
	v_mul_f32_e32 v48, v4, v48
	v_mul_f32_e32 v163, v6, v163
	v_cvt_pk_bf16_f32 v240, v46, v240
	v_cvt_pk_bf16_f32 v241, v47, v241
	v_cvt_pk_bf16_f32 v242, v48, v242
	v_cvt_pk_bf16_f32 v243, v163, v243
	ds_write_b128 v44, v[240:243] offset:8192
	ds_read_b128 v[28:31], v45 offset:2560
	ds_read_b128 v[168:171], v45 offset:2576
	s_waitcnt lgkmcnt(2)
	v_add_f32_e32 v164, v52, v53
	v_add_f32_e32 v165, v56, v57
	v_add_f32_e32 v166, v54, v55
	v_add_f32_e32 v161, v58, v59
	v_add_f32_e32 v164, v164, v166
	v_add_f32_e32 v165, v165, v161
	v_add_f32_e32 v164, v164, v165
	v_fmamk_f32 v164, v164, 0x3b000000, v193
	v_rsq_f32_e32 v164, v164
	s_waitcnt vmcnt(6)
	v_lshlrev_b32_e32 v46, 16, v244
	v_lshlrev_b32_e32 v47, 16, v245
	v_lshlrev_b32_e32 v48, 16, v246
	v_lshlrev_b32_e32 v163, 16, v247
	v_and_b32_e32 v244, 0xffff0000, v244
	v_and_b32_e32 v245, 0xffff0000, v245
	v_and_b32_e32 v246, 0xffff0000, v246
	v_and_b32_e32 v247, 0xffff0000, v247
	v_mul_f32_e32 v244, v164, v244
	v_mul_f32_e32 v245, v164, v245
	v_mul_f32_e32 v246, v164, v246
	v_mul_f32_e32 v247, v164, v247
	v_mul_f32_e32 v46, v164, v46
	v_mul_f32_e32 v47, v164, v47
	v_mul_f32_e32 v48, v164, v48
	v_mul_f32_e32 v163, v164, v163
	v_mul_f32_e32 v244, v9, v244
	v_mul_f32_e32 v245, v11, v245
	v_mul_f32_e32 v246, v5, v246
	v_mul_f32_e32 v247, v7, v247
	v_mul_f32_e32 v46, v8, v46
	v_mul_f32_e32 v47, v10, v47
	v_mul_f32_e32 v48, v4, v48
	v_mul_f32_e32 v163, v6, v163
	v_cvt_pk_bf16_f32 v244, v46, v244
	v_cvt_pk_bf16_f32 v245, v47, v245
	v_cvt_pk_bf16_f32 v246, v48, v246
	v_cvt_pk_bf16_f32 v247, v163, v247
	ds_write_b128 v44, v[244:247] offset:9216
	ds_read_b128 v[52:55], v45 offset:2816
	ds_read_b128 v[56:59], v45 offset:2832
	s_waitcnt lgkmcnt(2)
	v_add_f32_e32 v164, v28, v29
	v_add_f32_e32 v165, v168, v169
	v_add_f32_e32 v166, v30, v31
	v_add_f32_e32 v161, v170, v171
	v_add_f32_e32 v164, v164, v166
	v_add_f32_e32 v165, v165, v161
	v_add_f32_e32 v164, v164, v165
	v_fmamk_f32 v164, v164, 0x3b000000, v193
	v_rsq_f32_e32 v164, v164
	s_waitcnt vmcnt(5)
	v_lshlrev_b32_e32 v46, 16, v248
	v_lshlrev_b32_e32 v47, 16, v249
	v_lshlrev_b32_e32 v48, 16, v250
	v_lshlrev_b32_e32 v163, 16, v251
	v_and_b32_e32 v248, 0xffff0000, v248
	v_and_b32_e32 v249, 0xffff0000, v249
	v_and_b32_e32 v250, 0xffff0000, v250
	v_and_b32_e32 v251, 0xffff0000, v251
	v_mul_f32_e32 v248, v164, v248
	v_mul_f32_e32 v249, v164, v249
	v_mul_f32_e32 v250, v164, v250
	v_mul_f32_e32 v251, v164, v251
	v_mul_f32_e32 v46, v164, v46
	v_mul_f32_e32 v47, v164, v47
	v_mul_f32_e32 v48, v164, v48
	v_mul_f32_e32 v163, v164, v163
	v_mul_f32_e32 v248, v9, v248
	v_mul_f32_e32 v249, v11, v249
	v_mul_f32_e32 v250, v5, v250
	v_mul_f32_e32 v251, v7, v251
	v_mul_f32_e32 v46, v8, v46
	v_mul_f32_e32 v47, v10, v47
	v_mul_f32_e32 v48, v4, v48
	v_mul_f32_e32 v163, v6, v163
	v_cvt_pk_bf16_f32 v248, v46, v248
	v_cvt_pk_bf16_f32 v249, v47, v249
	v_cvt_pk_bf16_f32 v250, v48, v250
	v_cvt_pk_bf16_f32 v251, v163, v251
	ds_write_b128 v44, v[248:251] offset:10240
	ds_read_b128 v[28:31], v45 offset:3072
	ds_read_b128 v[168:171], v45 offset:3088
	s_waitcnt lgkmcnt(2)
	v_add_f32_e32 v164, v52, v53
	v_add_f32_e32 v165, v56, v57
	v_add_f32_e32 v166, v54, v55
	v_add_f32_e32 v161, v58, v59
	v_add_f32_e32 v164, v164, v166
	v_add_f32_e32 v165, v165, v161
	v_add_f32_e32 v164, v164, v165
	v_fmamk_f32 v164, v164, 0x3b000000, v193
	v_rsq_f32_e32 v164, v164
	s_waitcnt vmcnt(4)
	v_lshlrev_b32_e32 v46, 16, v32
	v_lshlrev_b32_e32 v47, 16, v33
	v_lshlrev_b32_e32 v48, 16, v34
	v_lshlrev_b32_e32 v163, 16, v35
	v_and_b32_e32 v32, 0xffff0000, v32
	v_and_b32_e32 v33, 0xffff0000, v33
	v_and_b32_e32 v34, 0xffff0000, v34
	v_and_b32_e32 v35, 0xffff0000, v35
	v_mul_f32_e32 v32, v164, v32
	v_mul_f32_e32 v33, v164, v33
	v_mul_f32_e32 v34, v164, v34
	v_mul_f32_e32 v35, v164, v35
	v_mul_f32_e32 v46, v164, v46
	v_mul_f32_e32 v47, v164, v47
	v_mul_f32_e32 v48, v164, v48
	v_mul_f32_e32 v163, v164, v163
	v_mul_f32_e32 v32, v9, v32
	v_mul_f32_e32 v33, v11, v33
	v_mul_f32_e32 v34, v5, v34
	v_mul_f32_e32 v35, v7, v35
	v_mul_f32_e32 v46, v8, v46
	v_mul_f32_e32 v47, v10, v47
	v_mul_f32_e32 v48, v4, v48
	v_mul_f32_e32 v163, v6, v163
	v_cvt_pk_bf16_f32 v32, v46, v32
	v_cvt_pk_bf16_f32 v33, v47, v33
	v_cvt_pk_bf16_f32 v34, v48, v34
	v_cvt_pk_bf16_f32 v35, v163, v35
	ds_write_b128 v44, v[32:35] offset:11264
	ds_read_b128 v[52:55], v45 offset:3328
	ds_read_b128 v[56:59], v45 offset:3344
	s_waitcnt lgkmcnt(2)
	v_add_f32_e32 v164, v28, v29
	v_add_f32_e32 v165, v168, v169
	v_add_f32_e32 v166, v30, v31
	v_add_f32_e32 v161, v170, v171
	v_add_f32_e32 v164, v164, v166
	v_add_f32_e32 v165, v165, v161
	v_add_f32_e32 v164, v164, v165
	v_fmamk_f32 v164, v164, 0x3b000000, v193
	v_rsq_f32_e32 v164, v164
	s_waitcnt vmcnt(3)
	v_lshlrev_b32_e32 v46, 16, v36
	v_lshlrev_b32_e32 v47, 16, v37
	v_lshlrev_b32_e32 v48, 16, v38
	v_lshlrev_b32_e32 v163, 16, v39
	v_and_b32_e32 v36, 0xffff0000, v36
	v_and_b32_e32 v37, 0xffff0000, v37
	v_and_b32_e32 v38, 0xffff0000, v38
	v_and_b32_e32 v39, 0xffff0000, v39
	v_mul_f32_e32 v36, v164, v36
	v_mul_f32_e32 v37, v164, v37
	v_mul_f32_e32 v38, v164, v38
	v_mul_f32_e32 v39, v164, v39
	v_mul_f32_e32 v46, v164, v46
	v_mul_f32_e32 v47, v164, v47
	v_mul_f32_e32 v48, v164, v48
	v_mul_f32_e32 v163, v164, v163
	v_mul_f32_e32 v36, v9, v36
	v_mul_f32_e32 v37, v11, v37
	v_mul_f32_e32 v38, v5, v38
	v_mul_f32_e32 v39, v7, v39
	v_mul_f32_e32 v46, v8, v46
	v_mul_f32_e32 v47, v10, v47
	v_mul_f32_e32 v48, v4, v48
	v_mul_f32_e32 v163, v6, v163
	v_cvt_pk_bf16_f32 v36, v46, v36
	v_cvt_pk_bf16_f32 v37, v47, v37
	v_cvt_pk_bf16_f32 v38, v48, v38
	v_cvt_pk_bf16_f32 v39, v163, v39
	ds_write_b128 v44, v[36:39] offset:12288
	ds_read_b128 v[28:31], v45 offset:3584
	ds_read_b128 v[168:171], v45 offset:3600
	s_waitcnt lgkmcnt(2)
	v_add_f32_e32 v164, v52, v53
	v_add_f32_e32 v165, v56, v57
	v_add_f32_e32 v166, v54, v55
	v_add_f32_e32 v161, v58, v59
	v_add_f32_e32 v164, v164, v166
	v_add_f32_e32 v165, v165, v161
	v_add_f32_e32 v164, v164, v165
	v_fmamk_f32 v164, v164, 0x3b000000, v193
	v_rsq_f32_e32 v164, v164
	s_waitcnt vmcnt(2)
	v_lshlrev_b32_e32 v46, 16, v40
	v_lshlrev_b32_e32 v47, 16, v41
	v_lshlrev_b32_e32 v48, 16, v42
	v_lshlrev_b32_e32 v163, 16, v43
	v_and_b32_e32 v40, 0xffff0000, v40
	v_and_b32_e32 v41, 0xffff0000, v41
	v_and_b32_e32 v42, 0xffff0000, v42
	v_and_b32_e32 v43, 0xffff0000, v43
	v_mul_f32_e32 v40, v164, v40
	v_mul_f32_e32 v41, v164, v41
	v_mul_f32_e32 v42, v164, v42
	v_mul_f32_e32 v43, v164, v43
	v_mul_f32_e32 v46, v164, v46
	v_mul_f32_e32 v47, v164, v47
	v_mul_f32_e32 v48, v164, v48
	v_mul_f32_e32 v163, v164, v163
	v_mul_f32_e32 v40, v9, v40
	v_mul_f32_e32 v41, v11, v41
	v_mul_f32_e32 v42, v5, v42
	v_mul_f32_e32 v43, v7, v43
	v_mul_f32_e32 v46, v8, v46
	v_mul_f32_e32 v47, v10, v47
	v_mul_f32_e32 v48, v4, v48
	v_mul_f32_e32 v163, v6, v163
	v_cvt_pk_bf16_f32 v40, v46, v40
	v_cvt_pk_bf16_f32 v41, v47, v41
	v_cvt_pk_bf16_f32 v42, v48, v42
	v_cvt_pk_bf16_f32 v43, v163, v43
	ds_write_b128 v44, v[40:43] offset:13312
	ds_read_b128 v[52:55], v45 offset:3840
	ds_read_b128 v[56:59], v45 offset:3856
	s_waitcnt lgkmcnt(2)
	v_add_f32_e32 v164, v28, v29
	v_add_f32_e32 v165, v168, v169
	v_add_f32_e32 v166, v30, v31
	v_add_f32_e32 v161, v170, v171
	v_add_f32_e32 v164, v164, v166
	v_add_f32_e32 v165, v165, v161
	v_add_f32_e32 v164, v164, v165
	v_fmamk_f32 v164, v164, 0x3b000000, v193
	v_rsq_f32_e32 v164, v164
	s_waitcnt vmcnt(1)
	v_lshlrev_b32_e32 v46, 16, v24
	v_lshlrev_b32_e32 v47, 16, v25
	v_lshlrev_b32_e32 v48, 16, v26
	v_lshlrev_b32_e32 v163, 16, v27
	v_and_b32_e32 v24, 0xffff0000, v24
	v_and_b32_e32 v25, 0xffff0000, v25
	v_and_b32_e32 v26, 0xffff0000, v26
	v_and_b32_e32 v27, 0xffff0000, v27
	v_mul_f32_e32 v24, v164, v24
	v_mul_f32_e32 v25, v164, v25
	v_mul_f32_e32 v26, v164, v26
	v_mul_f32_e32 v27, v164, v27
	v_mul_f32_e32 v46, v164, v46
	v_mul_f32_e32 v47, v164, v47
	v_mul_f32_e32 v48, v164, v48
	v_mul_f32_e32 v163, v164, v163
	v_mul_f32_e32 v24, v9, v24
	v_mul_f32_e32 v25, v11, v25
	v_mul_f32_e32 v26, v5, v26
	v_mul_f32_e32 v27, v7, v27
	v_mul_f32_e32 v46, v8, v46
	v_mul_f32_e32 v47, v10, v47
	v_mul_f32_e32 v48, v4, v48
	v_mul_f32_e32 v163, v6, v163
	v_cvt_pk_bf16_f32 v24, v46, v24
	v_cvt_pk_bf16_f32 v25, v47, v25
	v_cvt_pk_bf16_f32 v26, v48, v26
	v_cvt_pk_bf16_f32 v27, v163, v27
	ds_write_b128 v44, v[24:27] offset:14336
	s_waitcnt lgkmcnt(0)
	v_add_f32_e32 v164, v52, v53
	v_add_f32_e32 v165, v56, v57
	v_add_f32_e32 v166, v54, v55
	v_add_f32_e32 v161, v58, v59
	v_add_f32_e32 v164, v164, v166
	v_add_f32_e32 v165, v165, v161
	v_add_f32_e32 v164, v164, v165
	v_fmamk_f32 v164, v164, 0x3b000000, v193
	v_rsq_f32_e32 v164, v164
	s_waitcnt vmcnt(0)
	v_lshlrev_b32_e32 v46, 16, v186
	v_lshlrev_b32_e32 v47, 16, v187
	v_lshlrev_b32_e32 v48, 16, v188
	v_lshlrev_b32_e32 v163, 16, v189
	v_and_b32_e32 v186, 0xffff0000, v186
	v_and_b32_e32 v187, 0xffff0000, v187
	v_and_b32_e32 v188, 0xffff0000, v188
	v_and_b32_e32 v189, 0xffff0000, v189
	v_mul_f32_e32 v186, v164, v186
	v_mul_f32_e32 v187, v164, v187
	v_mul_f32_e32 v188, v164, v188
	v_mul_f32_e32 v189, v164, v189
	v_mul_f32_e32 v46, v164, v46
	v_mul_f32_e32 v47, v164, v47
	v_mul_f32_e32 v48, v164, v48
	v_mul_f32_e32 v163, v164, v163
	v_mul_f32_e32 v186, v9, v186
	v_mul_f32_e32 v187, v11, v187
	v_mul_f32_e32 v188, v5, v188
	v_mul_f32_e32 v189, v7, v189
	v_mul_f32_e32 v46, v8, v46
	v_mul_f32_e32 v47, v10, v47
	v_mul_f32_e32 v48, v4, v48
	v_mul_f32_e32 v163, v6, v163
	v_cvt_pk_bf16_f32 v186, v46, v186
	v_cvt_pk_bf16_f32 v187, v47, v187
	v_cvt_pk_bf16_f32 v188, v48, v188
	v_cvt_pk_bf16_f32 v189, v163, v189
	ds_write_b128 v44, v[186:189] offset:15360
	s_branch .LBB0_560
.Lsgu_single:
	v_add_co_u32_e32 v252, vcc, 0x1000, v20
	s_nop 1
	v_addc_co_u32_e32 v253, vcc, 0, v21, vcc
	global_load_dwordx4 v[208:211], v[252:253], off
	v_add_co_u32_e32 v252, vcc, 0xb000, v20
	s_nop 1
	v_addc_co_u32_e32 v253, vcc, 0, v21, vcc
	global_load_dwordx4 v[212:215], v[252:253], off
	v_add_co_u32_e32 v252, vcc, 0x15000, v20
	s_nop 1
	v_addc_co_u32_e32 v253, vcc, 0, v21, vcc
	global_load_dwordx4 v[216:219], v[252:253], off
	v_add_co_u32_e32 v252, vcc, 0x1f000, v20
	s_nop 1
	v_addc_co_u32_e32 v253, vcc, 0, v21, vcc
	global_load_dwordx4 v[220:223], v[252:253], off
	v_add_co_u32_e32 v252, vcc, 0x29000, v20
	s_nop 1
	v_addc_co_u32_e32 v253, vcc, 0, v21, vcc
	global_load_dwordx4 v[224:227], v[252:253], off
	v_add_co_u32_e32 v252, vcc, 0x33000, v20
	s_nop 1
	v_addc_co_u32_e32 v253, vcc, 0, v21, vcc
	global_load_dwordx4 v[228:231], v[252:253], off
	v_add_co_u32_e32 v252, vcc, 0x3d000, v20
	s_nop 1
	v_addc_co_u32_e32 v253, vcc, 0, v21, vcc
	global_load_dwordx4 v[232:235], v[252:253], off
	v_add_co_u32_e32 v252, vcc, 0x47000, v20
	s_nop 1
	v_addc_co_u32_e32 v253, vcc, 0, v21, vcc
	global_load_dwordx4 v[236:239], v[252:253], off
	ds_read_b128 v[28:31], v45
	ds_read_b128 v[168:171], v45 offset:16
	ds_read_b128 v[52:55], v45 offset:256
	ds_read_b128 v[56:59], v45 offset:272
	s_waitcnt lgkmcnt(2)
	v_add_f32_e32 v164, v28, v29
	v_add_f32_e32 v165, v168, v169
	v_add_f32_e32 v166, v30, v31
	v_add_f32_e32 v161, v170, v171
	v_add_f32_e32 v164, v164, v166
	v_add_f32_e32 v165, v165, v161
	v_add_f32_e32 v164, v164, v165
	v_fmamk_f32 v164, v164, 0x3b000000, v193
	v_rsq_f32_e32 v164, v164
	s_waitcnt vmcnt(7)
	v_lshlrev_b32_e32 v46, 16, v208
	v_lshlrev_b32_e32 v47, 16, v209
	v_lshlrev_b32_e32 v48, 16, v210
	v_lshlrev_b32_e32 v163, 16, v211
	v_and_b32_e32 v208, 0xffff0000, v208
	v_and_b32_e32 v209, 0xffff0000, v209
	v_and_b32_e32 v210, 0xffff0000, v210
	v_and_b32_e32 v211, 0xffff0000, v211
	v_mul_f32_e32 v208, v164, v208
	v_mul_f32_e32 v209, v164, v209
	v_mul_f32_e32 v210, v164, v210
	v_mul_f32_e32 v211, v164, v211
	v_mul_f32_e32 v46, v164, v46
	v_mul_f32_e32 v47, v164, v47
	v_mul_f32_e32 v48, v164, v48
	v_mul_f32_e32 v163, v164, v163
	v_mul_f32_e32 v208, v9, v208
	v_mul_f32_e32 v209, v11, v209
	v_mul_f32_e32 v210, v5, v210
	v_mul_f32_e32 v211, v7, v211
	v_mul_f32_e32 v46, v8, v46
	v_mul_f32_e32 v47, v10, v47
	v_mul_f32_e32 v48, v4, v48
	v_mul_f32_e32 v163, v6, v163
	v_cvt_pk_bf16_f32 v208, v46, v208
	v_cvt_pk_bf16_f32 v209, v47, v209
	v_cvt_pk_bf16_f32 v210, v48, v210
	v_cvt_pk_bf16_f32 v211, v163, v211
	ds_write_b128 v44, v[208:211]
	ds_read_b128 v[28:31], v45 offset:512
	ds_read_b128 v[168:171], v45 offset:528
	s_waitcnt lgkmcnt(2)
	v_add_f32_e32 v164, v52, v53
	v_add_f32_e32 v165, v56, v57
	v_add_f32_e32 v166, v54, v55
	v_add_f32_e32 v161, v58, v59
	v_add_f32_e32 v164, v164, v166
	v_add_f32_e32 v165, v165, v161
	v_add_f32_e32 v164, v164, v165
	v_fmamk_f32 v164, v164, 0x3b000000, v193
	v_rsq_f32_e32 v164, v164
	s_waitcnt vmcnt(6)
	v_lshlrev_b32_e32 v46, 16, v212
	v_lshlrev_b32_e32 v47, 16, v213
	v_lshlrev_b32_e32 v48, 16, v214
	v_lshlrev_b32_e32 v163, 16, v215
	v_and_b32_e32 v212, 0xffff0000, v212
	v_and_b32_e32 v213, 0xffff0000, v213
	v_and_b32_e32 v214, 0xffff0000, v214
	v_and_b32_e32 v215, 0xffff0000, v215
	v_mul_f32_e32 v212, v164, v212
	v_mul_f32_e32 v213, v164, v213
	v_mul_f32_e32 v214, v164, v214
	v_mul_f32_e32 v215, v164, v215
	v_mul_f32_e32 v46, v164, v46
	v_mul_f32_e32 v47, v164, v47
	v_mul_f32_e32 v48, v164, v48
	v_mul_f32_e32 v163, v164, v163
	v_mul_f32_e32 v212, v9, v212
	v_mul_f32_e32 v213, v11, v213
	v_mul_f32_e32 v214, v5, v214
	v_mul_f32_e32 v215, v7, v215
	v_mul_f32_e32 v46, v8, v46
	v_mul_f32_e32 v47, v10, v47
	v_mul_f32_e32 v48, v4, v48
	v_mul_f32_e32 v163, v6, v163
	v_cvt_pk_bf16_f32 v212, v46, v212
	v_cvt_pk_bf16_f32 v213, v47, v213
	v_cvt_pk_bf16_f32 v214, v48, v214
	v_cvt_pk_bf16_f32 v215, v163, v215
	ds_write_b128 v44, v[212:215] offset:1024
	ds_read_b128 v[52:55], v45 offset:768
	ds_read_b128 v[56:59], v45 offset:784
	s_waitcnt lgkmcnt(2)
	v_add_f32_e32 v164, v28, v29
	v_add_f32_e32 v165, v168, v169
	v_add_f32_e32 v166, v30, v31
	v_add_f32_e32 v161, v170, v171
	v_add_f32_e32 v164, v164, v166
	v_add_f32_e32 v165, v165, v161
	v_add_f32_e32 v164, v164, v165
	v_fmamk_f32 v164, v164, 0x3b000000, v193
	v_rsq_f32_e32 v164, v164
	s_waitcnt vmcnt(5)
	v_lshlrev_b32_e32 v46, 16, v216
	v_lshlrev_b32_e32 v47, 16, v217
	v_lshlrev_b32_e32 v48, 16, v218
	v_lshlrev_b32_e32 v163, 16, v219
	v_and_b32_e32 v216, 0xffff0000, v216
	v_and_b32_e32 v217, 0xffff0000, v217
	v_and_b32_e32 v218, 0xffff0000, v218
	v_and_b32_e32 v219, 0xffff0000, v219
	v_mul_f32_e32 v216, v164, v216
	v_mul_f32_e32 v217, v164, v217
	v_mul_f32_e32 v218, v164, v218
	v_mul_f32_e32 v219, v164, v219
	v_mul_f32_e32 v46, v164, v46
	v_mul_f32_e32 v47, v164, v47
	v_mul_f32_e32 v48, v164, v48
	v_mul_f32_e32 v163, v164, v163
	v_mul_f32_e32 v216, v9, v216
	v_mul_f32_e32 v217, v11, v217
	v_mul_f32_e32 v218, v5, v218
	v_mul_f32_e32 v219, v7, v219
	v_mul_f32_e32 v46, v8, v46
	v_mul_f32_e32 v47, v10, v47
	v_mul_f32_e32 v48, v4, v48
	v_mul_f32_e32 v163, v6, v163
	v_cvt_pk_bf16_f32 v216, v46, v216
	v_cvt_pk_bf16_f32 v217, v47, v217
	v_cvt_pk_bf16_f32 v218, v48, v218
	v_cvt_pk_bf16_f32 v219, v163, v219
	ds_write_b128 v44, v[216:219] offset:2048
	ds_read_b128 v[28:31], v45 offset:1024
	ds_read_b128 v[168:171], v45 offset:1040
	s_waitcnt lgkmcnt(2)
	v_add_f32_e32 v164, v52, v53
	v_add_f32_e32 v165, v56, v57
	v_add_f32_e32 v166, v54, v55
	v_add_f32_e32 v161, v58, v59
	v_add_f32_e32 v164, v164, v166
	v_add_f32_e32 v165, v165, v161
	v_add_f32_e32 v164, v164, v165
	v_fmamk_f32 v164, v164, 0x3b000000, v193
	v_rsq_f32_e32 v164, v164
	s_waitcnt vmcnt(4)
	v_lshlrev_b32_e32 v46, 16, v220
	v_lshlrev_b32_e32 v47, 16, v221
	v_lshlrev_b32_e32 v48, 16, v222
	v_lshlrev_b32_e32 v163, 16, v223
	v_and_b32_e32 v220, 0xffff0000, v220
	v_and_b32_e32 v221, 0xffff0000, v221
	v_and_b32_e32 v222, 0xffff0000, v222
	v_and_b32_e32 v223, 0xffff0000, v223
	v_mul_f32_e32 v220, v164, v220
	v_mul_f32_e32 v221, v164, v221
	v_mul_f32_e32 v222, v164, v222
	v_mul_f32_e32 v223, v164, v223
	v_mul_f32_e32 v46, v164, v46
	v_mul_f32_e32 v47, v164, v47
	v_mul_f32_e32 v48, v164, v48
	v_mul_f32_e32 v163, v164, v163
	v_mul_f32_e32 v220, v9, v220
	v_mul_f32_e32 v221, v11, v221
	v_mul_f32_e32 v222, v5, v222
	v_mul_f32_e32 v223, v7, v223
	v_mul_f32_e32 v46, v8, v46
	v_mul_f32_e32 v47, v10, v47
	v_mul_f32_e32 v48, v4, v48
	v_mul_f32_e32 v163, v6, v163
	v_cvt_pk_bf16_f32 v220, v46, v220
	v_cvt_pk_bf16_f32 v221, v47, v221
	v_cvt_pk_bf16_f32 v222, v48, v222
	v_cvt_pk_bf16_f32 v223, v163, v223
	ds_write_b128 v44, v[220:223] offset:3072
	ds_read_b128 v[52:55], v45 offset:1280
	ds_read_b128 v[56:59], v45 offset:1296
	s_waitcnt lgkmcnt(2)
	v_add_f32_e32 v164, v28, v29
	v_add_f32_e32 v165, v168, v169
	v_add_f32_e32 v166, v30, v31
	v_add_f32_e32 v161, v170, v171
	v_add_f32_e32 v164, v164, v166
	v_add_f32_e32 v165, v165, v161
	v_add_f32_e32 v164, v164, v165
	v_fmamk_f32 v164, v164, 0x3b000000, v193
	v_rsq_f32_e32 v164, v164
	s_waitcnt vmcnt(3)
	v_lshlrev_b32_e32 v46, 16, v224
	v_lshlrev_b32_e32 v47, 16, v225
	v_lshlrev_b32_e32 v48, 16, v226
	v_lshlrev_b32_e32 v163, 16, v227
	v_and_b32_e32 v224, 0xffff0000, v224
	v_and_b32_e32 v225, 0xffff0000, v225
	v_and_b32_e32 v226, 0xffff0000, v226
	v_and_b32_e32 v227, 0xffff0000, v227
	v_mul_f32_e32 v224, v164, v224
	v_mul_f32_e32 v225, v164, v225
	v_mul_f32_e32 v226, v164, v226
	v_mul_f32_e32 v227, v164, v227
	v_mul_f32_e32 v46, v164, v46
	v_mul_f32_e32 v47, v164, v47
	v_mul_f32_e32 v48, v164, v48
	v_mul_f32_e32 v163, v164, v163
	v_mul_f32_e32 v224, v9, v224
	v_mul_f32_e32 v225, v11, v225
	v_mul_f32_e32 v226, v5, v226
	v_mul_f32_e32 v227, v7, v227
	v_mul_f32_e32 v46, v8, v46
	v_mul_f32_e32 v47, v10, v47
	v_mul_f32_e32 v48, v4, v48
	v_mul_f32_e32 v163, v6, v163
	v_cvt_pk_bf16_f32 v224, v46, v224
	v_cvt_pk_bf16_f32 v225, v47, v225
	v_cvt_pk_bf16_f32 v226, v48, v226
	v_cvt_pk_bf16_f32 v227, v163, v227
	ds_write_b128 v44, v[224:227] offset:4096
	ds_read_b128 v[28:31], v45 offset:1536
	ds_read_b128 v[168:171], v45 offset:1552
	s_waitcnt lgkmcnt(2)
	v_add_f32_e32 v164, v52, v53
	v_add_f32_e32 v165, v56, v57
	v_add_f32_e32 v166, v54, v55
	v_add_f32_e32 v161, v58, v59
	v_add_f32_e32 v164, v164, v166
	v_add_f32_e32 v165, v165, v161
	v_add_f32_e32 v164, v164, v165
	v_fmamk_f32 v164, v164, 0x3b000000, v193
	v_rsq_f32_e32 v164, v164
	s_waitcnt vmcnt(2)
	v_lshlrev_b32_e32 v46, 16, v228
	v_lshlrev_b32_e32 v47, 16, v229
	v_lshlrev_b32_e32 v48, 16, v230
	v_lshlrev_b32_e32 v163, 16, v231
	v_and_b32_e32 v228, 0xffff0000, v228
	v_and_b32_e32 v229, 0xffff0000, v229
	v_and_b32_e32 v230, 0xffff0000, v230
	v_and_b32_e32 v231, 0xffff0000, v231
	v_mul_f32_e32 v228, v164, v228
	v_mul_f32_e32 v229, v164, v229
	v_mul_f32_e32 v230, v164, v230
	v_mul_f32_e32 v231, v164, v231
	v_mul_f32_e32 v46, v164, v46
	v_mul_f32_e32 v47, v164, v47
	v_mul_f32_e32 v48, v164, v48
	v_mul_f32_e32 v163, v164, v163
	v_mul_f32_e32 v228, v9, v228
	v_mul_f32_e32 v229, v11, v229
	v_mul_f32_e32 v230, v5, v230
	v_mul_f32_e32 v231, v7, v231
	v_mul_f32_e32 v46, v8, v46
	v_mul_f32_e32 v47, v10, v47
	v_mul_f32_e32 v48, v4, v48
	v_mul_f32_e32 v163, v6, v163
	v_cvt_pk_bf16_f32 v228, v46, v228
	v_cvt_pk_bf16_f32 v229, v47, v229
	v_cvt_pk_bf16_f32 v230, v48, v230
	v_cvt_pk_bf16_f32 v231, v163, v231
	ds_write_b128 v44, v[228:231] offset:5120
	ds_read_b128 v[52:55], v45 offset:1792
	ds_read_b128 v[56:59], v45 offset:1808
	s_waitcnt lgkmcnt(2)
	v_add_f32_e32 v164, v28, v29
	v_add_f32_e32 v165, v168, v169
	v_add_f32_e32 v166, v30, v31
	v_add_f32_e32 v161, v170, v171
	v_add_f32_e32 v164, v164, v166
	v_add_f32_e32 v165, v165, v161
	v_add_f32_e32 v164, v164, v165
	v_fmamk_f32 v164, v164, 0x3b000000, v193
	v_rsq_f32_e32 v164, v164
	s_waitcnt vmcnt(1)
	v_lshlrev_b32_e32 v46, 16, v232
	v_lshlrev_b32_e32 v47, 16, v233
	v_lshlrev_b32_e32 v48, 16, v234
	v_lshlrev_b32_e32 v163, 16, v235
	v_and_b32_e32 v232, 0xffff0000, v232
	v_and_b32_e32 v233, 0xffff0000, v233
	v_and_b32_e32 v234, 0xffff0000, v234
	v_and_b32_e32 v235, 0xffff0000, v235
	v_mul_f32_e32 v232, v164, v232
	v_mul_f32_e32 v233, v164, v233
	v_mul_f32_e32 v234, v164, v234
	v_mul_f32_e32 v235, v164, v235
	v_mul_f32_e32 v46, v164, v46
	v_mul_f32_e32 v47, v164, v47
	v_mul_f32_e32 v48, v164, v48
	v_mul_f32_e32 v163, v164, v163
	v_mul_f32_e32 v232, v9, v232
	v_mul_f32_e32 v233, v11, v233
	v_mul_f32_e32 v234, v5, v234
	v_mul_f32_e32 v235, v7, v235
	v_mul_f32_e32 v46, v8, v46
	v_mul_f32_e32 v47, v10, v47
	v_mul_f32_e32 v48, v4, v48
	v_mul_f32_e32 v163, v6, v163
	v_cvt_pk_bf16_f32 v232, v46, v232
	v_cvt_pk_bf16_f32 v233, v47, v233
	v_cvt_pk_bf16_f32 v234, v48, v234
	v_cvt_pk_bf16_f32 v235, v163, v235
	ds_write_b128 v44, v[232:235] offset:6144
	s_waitcnt lgkmcnt(0)
	v_add_f32_e32 v164, v52, v53
	v_add_f32_e32 v165, v56, v57
	v_add_f32_e32 v166, v54, v55
	v_add_f32_e32 v161, v58, v59
	v_add_f32_e32 v164, v164, v166
	v_add_f32_e32 v165, v165, v161
	v_add_f32_e32 v164, v164, v165
	v_fmamk_f32 v164, v164, 0x3b000000, v193
	v_rsq_f32_e32 v164, v164
	s_waitcnt vmcnt(0)
	v_lshlrev_b32_e32 v46, 16, v236
	v_lshlrev_b32_e32 v47, 16, v237
	v_lshlrev_b32_e32 v48, 16, v238
	v_lshlrev_b32_e32 v163, 16, v239
	v_and_b32_e32 v236, 0xffff0000, v236
	v_and_b32_e32 v237, 0xffff0000, v237
	v_and_b32_e32 v238, 0xffff0000, v238
	v_and_b32_e32 v239, 0xffff0000, v239
	v_mul_f32_e32 v236, v164, v236
	v_mul_f32_e32 v237, v164, v237
	v_mul_f32_e32 v238, v164, v238
	v_mul_f32_e32 v239, v164, v239
	v_mul_f32_e32 v46, v164, v46
	v_mul_f32_e32 v47, v164, v47
	v_mul_f32_e32 v48, v164, v48
	v_mul_f32_e32 v163, v164, v163
	v_mul_f32_e32 v236, v9, v236
	v_mul_f32_e32 v237, v11, v237
	v_mul_f32_e32 v238, v5, v238
	v_mul_f32_e32 v239, v7, v239
	v_mul_f32_e32 v46, v8, v46
	v_mul_f32_e32 v47, v10, v47
	v_mul_f32_e32 v48, v4, v48
	v_mul_f32_e32 v163, v6, v163
	v_cvt_pk_bf16_f32 v236, v46, v236
	v_cvt_pk_bf16_f32 v237, v47, v237
	v_cvt_pk_bf16_f32 v238, v48, v238
	v_cvt_pk_bf16_f32 v239, v163, v239
	ds_write_b128 v44, v[236:239] offset:7168
.LBB0_560:
	v_lshrrev_b32_e32 v4, 2, v157
	v_lshlrev_b32_e32 v6, 3, v157
	v_and_or_b32 v4, v4, 3, v160
	v_lshlrev_b32_e32 v5, 1, v157
	v_and_b32_e32 v7, 24, v6
	v_lshlrev_b32_e32 v4, 7, v4
	v_and_or_b32 v5, v5, 32, v7
	v_and_b32_e32 v6, 64, v6
	v_or3_b32 v7, v6, v5, v4
	v_or_b32_e32 v5, 64, v5
	v_add_u32_e32 v163, s77, v7
	v_bitop3_b32 v8, v5, v4, v6 bitop3:0xde
	v_add_u32_e32 v161, s77, v8
	s_and_b64 vcc, exec, s[12:13]
	s_cbranch_vccnz .Lsgu_mm_short
	ds_read_b64_tr_b16 v[208:209], v163
	ds_read_b64_tr_b16 v[210:211], v163 offset:512
	ds_read_b64_tr_b16 v[212:213], v161
	ds_read_b64_tr_b16 v[214:215], v161 offset:512
	ds_read_b64_tr_b16 v[216:217], v163 offset:2048
	ds_read_b64_tr_b16 v[218:219], v163 offset:2560
	ds_read_b64_tr_b16 v[220:221], v161 offset:2048
	ds_read_b64_tr_b16 v[222:223], v161 offset:2560
	s_waitcnt lgkmcnt(4)
	v_mfma_f32_32x32x16_bf16 v[52:67], v[208:211], v[12:15], 0
	v_mfma_f32_32x32x16_bf16 v[20:35], v[208:211], v[16:19], 0
	v_mfma_f32_32x32x16_bf16 v[36:51], v[212:215], v[12:15], 0
	v_mfma_f32_32x32x16_bf16 v[4:19], v[212:215], v[16:19], 0
	ds_read_b64_tr_b16 v[224:225], v163 offset:4096
	ds_read_b64_tr_b16 v[226:227], v163 offset:4608
	ds_read_b64_tr_b16 v[228:229], v161 offset:4096
	ds_read_b64_tr_b16 v[230:231], v161 offset:4608
	s_waitcnt lgkmcnt(4)
	v_mfma_f32_32x32x16_bf16 v[52:67], v[216:219], v[148:151], v[52:67]
	v_mfma_f32_32x32x16_bf16 v[20:35], v[216:219], v[152:155], v[20:35]
	v_mfma_f32_32x32x16_bf16 v[36:51], v[220:223], v[148:151], v[36:51]
	v_mfma_f32_32x32x16_bf16 v[4:19], v[220:223], v[152:155], v[4:19]
	ds_read_b64_tr_b16 v[232:233], v163 offset:6144
	ds_read_b64_tr_b16 v[234:235], v163 offset:6656
	ds_read_b64_tr_b16 v[236:237], v161 offset:6144
	ds_read_b64_tr_b16 v[238:239], v161 offset:6656
	s_waitcnt lgkmcnt(4)
	v_mfma_f32_32x32x16_bf16 v[52:67], v[224:227], v[140:143], v[52:67]
	v_mfma_f32_32x32x16_bf16 v[20:35], v[224:227], v[144:147], v[20:35]
	v_mfma_f32_32x32x16_bf16 v[36:51], v[228:231], v[140:143], v[36:51]
	v_mfma_f32_32x32x16_bf16 v[4:19], v[228:231], v[144:147], v[4:19]
	ds_read_b64_tr_b16 v[208:209], v163 offset:8192
	ds_read_b64_tr_b16 v[210:211], v163 offset:8704
	ds_read_b64_tr_b16 v[212:213], v161 offset:8192
	ds_read_b64_tr_b16 v[214:215], v161 offset:8704
	s_waitcnt lgkmcnt(4)
	v_mfma_f32_32x32x16_bf16 v[52:67], v[232:235], v[132:135], v[52:67]
	v_mfma_f32_32x32x16_bf16 v[20:35], v[232:235], v[136:139], v[20:35]
	v_mfma_f32_32x32x16_bf16 v[36:51], v[236:239], v[132:135], v[36:51]
	v_mfma_f32_32x32x16_bf16 v[4:19], v[236:239], v[136:139], v[4:19]
	ds_read_b64_tr_b16 v[216:217], v163 offset:10240
	ds_read_b64_tr_b16 v[218:219], v163 offset:10752
	ds_read_b64_tr_b16 v[220:221], v161 offset:10240
	ds_read_b64_tr_b16 v[222:223], v161 offset:10752
	s_waitcnt lgkmcnt(4)
	v_mfma_f32_32x32x16_bf16 v[52:67], v[208:211], v[116:119], v[52:67]
	v_mfma_f32_32x32x16_bf16 v[20:35], v[208:211], v[120:123], v[20:35]
	v_mfma_f32_32x32x16_bf16 v[36:51], v[212:215], v[116:119], v[36:51]
	v_mfma_f32_32x32x16_bf16 v[4:19], v[212:215], v[120:123], v[4:19]
	ds_read_b64_tr_b16 v[224:225], v163 offset:12288
	ds_read_b64_tr_b16 v[226:227], v163 offset:12800
	ds_read_b64_tr_b16 v[228:229], v161 offset:12288
	ds_read_b64_tr_b16 v[230:231], v161 offset:12800
	s_waitcnt lgkmcnt(4)
	v_mfma_f32_32x32x16_bf16 v[52:67], v[216:219], v[100:103], v[52:67]
	v_mfma_f32_32x32x16_bf16 v[20:35], v[216:219], v[104:107], v[20:35]
	v_mfma_f32_32x32x16_bf16 v[36:51], v[220:223], v[100:103], v[36:51]
	v_mfma_f32_32x32x16_bf16 v[4:19], v[220:223], v[104:107], v[4:19]
	ds_read_b64_tr_b16 v[232:233], v163 offset:14336
	ds_read_b64_tr_b16 v[234:235], v163 offset:14848
	ds_read_b64_tr_b16 v[236:237], v161 offset:14336
	ds_read_b64_tr_b16 v[238:239], v161 offset:14848
	s_waitcnt lgkmcnt(4)
	v_mfma_f32_32x32x16_bf16 v[52:67], v[224:227], v[128:131], v[52:67]
	v_mfma_f32_32x32x16_bf16 v[20:35], v[224:227], v[124:127], v[20:35]
	v_mfma_f32_32x32x16_bf16 v[36:51], v[228:231], v[128:131], v[36:51]
	v_mfma_f32_32x32x16_bf16 v[4:19], v[228:231], v[124:127], v[4:19]
	s_waitcnt lgkmcnt(0)
	v_mfma_f32_32x32x16_bf16 v[52:67], v[232:235], v[112:115], v[52:67]
	v_mfma_f32_32x32x16_bf16 v[20:35], v[232:235], v[108:111], v[20:35]
	v_mfma_f32_32x32x16_bf16 v[36:51], v[236:239], v[112:115], v[36:51]
	v_mfma_f32_32x32x16_bf16 v[4:19], v[236:239], v[108:111], v[4:19]
	s_branch .LBB0_562
.Lsgu_mm_short:
	ds_read_b64_tr_b16 v[208:209], v163
	ds_read_b64_tr_b16 v[210:211], v163 offset:512
	ds_read_b64_tr_b16 v[212:213], v161
	ds_read_b64_tr_b16 v[214:215], v161 offset:512
	ds_read_b64_tr_b16 v[216:217], v163 offset:2048
	ds_read_b64_tr_b16 v[218:219], v163 offset:2560
	ds_read_b64_tr_b16 v[220:221], v161 offset:2048
	ds_read_b64_tr_b16 v[222:223], v161 offset:2560
	s_waitcnt lgkmcnt(4)
	v_mfma_f32_32x32x16_bf16 v[52:67], v[208:211], v[12:15], 0
	v_mfma_f32_32x32x16_bf16 v[20:35], v[208:211], v[16:19], 0
	v_mfma_f32_32x32x16_bf16 v[36:51], v[212:215], v[12:15], 0
	v_mfma_f32_32x32x16_bf16 v[4:19], v[212:215], v[16:19], 0
	ds_read_b64_tr_b16 v[224:225], v163 offset:4096
	ds_read_b64_tr_b16 v[226:227], v163 offset:4608
	ds_read_b64_tr_b16 v[228:229], v161 offset:4096
	ds_read_b64_tr_b16 v[230:231], v161 offset:4608
	s_waitcnt lgkmcnt(4)
	v_mfma_f32_32x32x16_bf16 v[52:67], v[216:219], v[148:151], v[52:67]
	v_mfma_f32_32x32x16_bf16 v[20:35], v[216:219], v[152:155], v[20:35]
	v_mfma_f32_32x32x16_bf16 v[36:51], v[220:223], v[148:151], v[36:51]
	v_mfma_f32_32x32x16_bf16 v[4:19], v[220:223], v[152:155], v[4:19]
	ds_read_b64_tr_b16 v[232:233], v163 offset:6144
	ds_read_b64_tr_b16 v[234:235], v163 offset:6656
	ds_read_b64_tr_b16 v[236:237], v161 offset:6144
	ds_read_b64_tr_b16 v[238:239], v161 offset:6656
	s_waitcnt lgkmcnt(4)
	v_mfma_f32_32x32x16_bf16 v[52:67], v[224:227], v[140:143], v[52:67]
	v_mfma_f32_32x32x16_bf16 v[20:35], v[224:227], v[144:147], v[20:35]
	v_mfma_f32_32x32x16_bf16 v[36:51], v[228:231], v[140:143], v[36:51]
	v_mfma_f32_32x32x16_bf16 v[4:19], v[228:231], v[144:147], v[4:19]
	s_waitcnt lgkmcnt(0)
	v_mfma_f32_32x32x16_bf16 v[52:67], v[232:235], v[132:135], v[52:67]
	v_mfma_f32_32x32x16_bf16 v[20:35], v[232:235], v[136:139], v[20:35]
	v_mfma_f32_32x32x16_bf16 v[36:51], v[236:239], v[132:135], v[36:51]
	v_mfma_f32_32x32x16_bf16 v[4:19], v[236:239], v[136:139], v[4:19]
